# combined: P4 epilogue SZ/gate loads issued together, sel skips never-read gathers (forced-visit B half, clamped slots) with count-matched waits, P8 unit loads software-pipelined one unit ahead
# speedup vs baseline: 1.0207x; 1.0140x over previous
.LBB0_422:
	s_or_b64 exec, exec, s[14:15]
	s_waitcnt vmcnt(1)
	v_or_b32_e32 v134, v202, v190
	v_mov_b32_e32 v135, v203
	v_lshl_add_u64 v[142:143], v[204:205], 2, s[58:59]
	v_lshlrev_b64 v[134:135], 1, v[134:135]
	global_load_dword v132, v[142:143], off
	v_lshl_add_u64 v[134:135], s[62:63], 0, v[134:135]
	v_or_b32_e32 v136, v202, v192
	v_mov_b32_e32 v137, v203
	global_load_dwordx2 v[124:125], v[134:135], off
	v_lshlrev_b64 v[136:137], 1, v[136:137]
	v_or_b32_e32 v138, v202, v194
	v_mov_b32_e32 v139, v203
	v_lshl_add_u64 v[136:137], s[62:63], 0, v[136:137]
	v_lshlrev_b64 v[138:139], 1, v[138:139]
	global_load_dwordx2 v[126:127], v[136:137], off
	v_lshl_add_u64 v[138:139], s[62:63], 0, v[138:139]
	v_or_b32_e32 v140, v202, v196
	v_mov_b32_e32 v141, v203
	global_load_dwordx2 v[128:129], v[138:139], off
	v_lshlrev_b64 v[140:141], 1, v[140:141]
	v_lshl_add_u64 v[140:141], s[62:63], 0, v[140:141]
	global_load_dwordx2 v[130:131], v[140:141], off
	v_or_b32_e32 v30, v202, v190
	v_mov_b32_e32 v31, v203
	v_lshlrev_b64 v[30:31], 1, v[30:31]
	ds_read2st64_b32 v[2:3], v213 offset1:1
	ds_read2st64_b32 v[12:13], v213 offset0:2 offset1:3
	ds_read2st64_b32 v[14:15], v213 offset0:4 offset1:5
	ds_read2st64_b32 v[16:17], v213 offset0:6 offset1:7
	ds_read2st64_b32 v[18:19], v213 offset0:8 offset1:9
	ds_read2st64_b32 v[24:25], v213 offset0:10 offset1:11
	ds_read2st64_b32 v[26:27], v213 offset0:12 offset1:13
	ds_read2st64_b32 v[28:29], v213 offset0:14 offset1:15
	ds_bpermute_b32 v34, v223, v234
	v_mov_b32_e32 v35, v203
	v_lshl_add_u64 v[30:31], s[48:49], 0, v[30:31]
	v_add_u32_e32 v226, s55, v226
	v_add_u32_e32 v225, s77, v225
	s_waitcnt lgkmcnt(0)
	v_add_f32_e32 v36, v234, v34
	ds_bpermute_b32 v37, v224, v36
	v_or_b32_e32 v34, v202, v192
	v_lshlrev_b64 v[34:35], 1, v[34:35]
	s_waitcnt lgkmcnt(0)
	v_add_f32_e32 v38, v36, v37
	v_div_scale_f32 v39, s[0:1], v38, v38, 1.0
	v_rcp_f32_e32 v40, v39
	v_div_scale_f32 v41, vcc, 1.0, v38, 1.0
	v_fma_f32 v42, -v39, v40, 1.0
	v_fmac_f32_e32 v40, v42, v40
	v_mul_f32_e32 v42, v41, v40
	v_fma_f32 v43, -v39, v42, v41
	v_fmac_f32_e32 v42, v43, v40
	v_fma_f32 v39, -v39, v42, v41
	v_div_fmas_f32 v39, v39, v40, v42
	v_div_fixup_f32 v39, v39, v38, 1.0
	v_cmp_lt_f32_e32 vcc, 0, v38
	s_waitcnt vmcnt(0)
	v_mov_b32_e32 v1, v132
	v_mov_b64_e32 v[32:33], v[124:125]
	v_lshlrev_b32_e32 v40, 16, v32
	v_cndmask_b32_e32 v38, 0, v39, vcc
	v_mul_f32_e32 v38, v1, v38
	v_pk_fma_f32 v[2:3], v[38:39], v[44:45], v[2:3] op_sel_hi:[0,1,1]
	v_pk_fma_f32 v[12:13], v[38:39], v[46:47], v[12:13] op_sel_hi:[0,1,1]
	v_and_b32_e32 v41, 0xffff0000, v32
	v_lshlrev_b32_e32 v32, 16, v33
	v_and_b32_e32 v33, 0xffff0000, v33
	v_pk_mul_f32 v[2:3], v[2:3], v[40:41]
	v_pk_mul_f32 v[12:13], v[12:13], v[32:33]
	v_cvt_pk_bf16_f32 v2, v2, v3
	v_cvt_pk_bf16_f32 v3, v12, v13
	global_store_dwordx2 v[30:31], v[2:3], off
	v_pk_fma_f32 v[14:15], v[38:39], v[20:21], v[14:15] op_sel_hi:[0,1,1]
	v_pk_fma_f32 v[16:17], v[38:39], v[22:23], v[16:17] op_sel_hi:[0,1,1]
	v_or_b32_e32 v12, v202, v194
	v_mov_b32_e32 v13, v203
	v_lshlrev_b64 v[12:13], 1, v[12:13]
	v_lshl_add_u64 v[30:31], s[48:49], 0, v[34:35]
	v_pk_fma_f32 v[4:5], v[38:39], v[4:5], v[18:19] op_sel_hi:[0,1,1]
	v_pk_fma_f32 v[6:7], v[38:39], v[6:7], v[24:25] op_sel_hi:[0,1,1]
	v_or_b32_e32 v202, v202, v196
	v_lshl_add_u64 v[12:13], s[48:49], 0, v[12:13]
	v_cmp_lt_i32_e32 vcc, s91, v226
	s_or_b64 s[80:81], vcc, s[80:81]
	v_mov_b64_e32 v[2:3], v[126:127]
	v_lshlrev_b32_e32 v20, 16, v2
	v_and_b32_e32 v21, 0xffff0000, v2
	v_lshlrev_b32_e32 v2, 16, v3
	v_and_b32_e32 v3, 0xffff0000, v3
	v_pk_mul_f32 v[14:15], v[14:15], v[20:21]
	v_pk_mul_f32 v[2:3], v[16:17], v[2:3]
	v_cvt_pk_bf16_f32 v14, v14, v15
	v_cvt_pk_bf16_f32 v15, v2, v3
	global_store_dwordx2 v[30:31], v[14:15], off
	v_lshlrev_b64 v[14:15], 1, v[202:203]
	v_mov_b64_e32 v[2:3], v[128:129]
	v_lshlrev_b32_e32 v18, 16, v2
	v_and_b32_e32 v19, 0xffff0000, v2
	v_lshlrev_b32_e32 v2, 16, v3
	v_and_b32_e32 v3, 0xffff0000, v3
	v_pk_mul_f32 v[4:5], v[4:5], v[18:19]
	v_pk_mul_f32 v[2:3], v[6:7], v[2:3]
	v_cvt_pk_bf16_f32 v4, v4, v5
	v_cvt_pk_bf16_f32 v5, v2, v3
	global_store_dwordx2 v[12:13], v[4:5], off
	v_pk_fma_f32 v[6:7], v[38:39], v[8:9], v[26:27] op_sel_hi:[0,1,1]
	v_pk_fma_f32 v[8:9], v[38:39], v[10:11], v[28:29] op_sel_hi:[0,1,1]
	v_lshl_add_u64 v[4:5], s[48:49], 0, v[14:15]
	v_mov_b64_e32 v[2:3], v[130:131]
	v_lshlrev_b32_e32 v10, 16, v2
	v_and_b32_e32 v11, 0xffff0000, v2
	v_lshlrev_b32_e32 v2, 16, v3
	v_and_b32_e32 v3, 0xffff0000, v3
	v_pk_mul_f32 v[6:7], v[6:7], v[10:11]
	v_pk_mul_f32 v[2:3], v[8:9], v[2:3]
	v_cvt_pk_bf16_f32 v6, v6, v7
	v_cvt_pk_bf16_f32 v7, v2, v3
	global_store_dwordx2 v[4:5], v[6:7], off
	s_andn2_b64 exec, exec, s[80:81]
	s_cbranch_execz .LBB0_418

.LBB0_569:
	s_or_b64 exec, exec, s[12:13]
	v_min_i32_e32 v153, 2, v229
	v_sub_u32_e32 v154, 15, v153
	v_lshlrev_b32_e32 v1, 1, v154
	v_add_u32_e32 v155, v1, v153
	s_waitcnt vmcnt(0)
	v_pk_mul_f32 v[14:15], v[2:3], v[14:15] op_sel_hi:[0,1]
	v_pk_mul_f32 v[12:13], v[2:3], v[12:13] op_sel_hi:[0,1]
	v_pk_mul_f32 v[48:49], v[2:3], v[26:27] op_sel_hi:[0,1]
	v_pk_mul_f32 v[28:29], v[2:3], v[24:25] op_sel_hi:[0,1]
	v_pk_mul_f32 v[26:27], v[2:3], v[22:23] op_sel_hi:[0,1]
	v_pk_mul_f32 v[52:53], v[2:3], v[20:21] op_sel_hi:[0,1]
	v_pk_mul_f32 v[24:25], v[2:3], v[18:19] op_sel_hi:[0,1]
	v_pk_mul_f32 v[50:51], v[2:3], v[16:17] op_sel_hi:[0,1]
	v_min_i32_e32 v2, 0, v155
	v_cmp_ge_i32_e32 vcc, v229, v2
	ds_write2st64_b32 v213, v12, v13 offset1:1
	ds_write2st64_b32 v213, v14, v15 offset0:2 offset1:3
	ds_write2st64_b32 v213, v28, v29 offset0:4 offset1:5
	ds_write2st64_b32 v213, v48, v49 offset0:6 offset1:7
	ds_write2st64_b32 v213, v52, v53 offset0:8 offset1:9
	ds_write2st64_b32 v213, v26, v27 offset0:10 offset1:11
	ds_write2st64_b32 v213, v50, v51 offset0:12 offset1:13
	ds_write2st64_b32 v213, v24, v25 offset0:14 offset1:15
	v_lshl_add_u32 v253, v207, 2, v210
	ds_read_b32 v252, v253 offset:5120
	v_readfirstlane_b32 s75, v229
	v_add_u32_e32 v230, 1, v153
	v_mov_b32_e32 v236, -1
	v_sub_u32_e32 v44, 0, v154
	v_mov_b32_e32 v235, 0
	v_mov_b32_e32 v234, 0
	s_min_i32 s32, s75, 2
	s_sub_i32 s36, 15, s32
	s_lshl_b32 s37, s36, 1
	s_add_i32 s37, s37, s32
	s_waitcnt lgkmcnt(0)
	v_mov_b32_e32 v2, v0
	v_mov_b32_e32 v3, v0
	v_add_u32_e32 v231, v1, v230
	v_mov_b32_e32 v1, v0
	v_mov_b64_e32 v[30:31], v[2:3]
	v_mov_b64_e32 v[34:35], v[2:3]
	v_mov_b64_e32 v[38:39], v[2:3]
	v_mov_b64_e32 v[42:43], v[2:3]
	v_cmp_lt_i32_e32 vcc, 0, v231
	v_mov_b32_e32 v237, 0
	v_mov_b64_e32 v[28:29], v[0:1]
	v_mov_b64_e32 v[32:33], v[0:1]
	v_mov_b64_e32 v[36:37], v[0:1]
	v_mov_b64_e32 v[40:41], v[0:1]
	s_and_saveexec_b64 s[16:17], vcc
	s_cbranch_execz .LBB0_607
	v_lshlrev_b32_e32 v2, 12, v235
	v_ashrrev_i32_e32 v3, 31, v2
	v_lshl_add_u64 v[12:13], v[198:199], 0, v[2:3]
	v_lshl_add_u64 v[2:3], v[200:201], 0, v[2:3]
	v_lshlrev_b32_e32 v2, 12, v234
	v_ashrrev_i32_e32 v3, 31, v2
	v_lshl_add_u64 v[24:25], v[198:199], 0, v[2:3]
	v_lshl_add_u64 v[2:3], v[200:201], 0, v[2:3]
	global_load_dwordx4 v[12:15], v[24:25], off offset:3072
	global_load_dwordx4 v[16:19], v[24:25], off offset:2048
	global_load_dwordx4 v[20:23], v[24:25], off offset:1024
	s_nop 0
	global_load_dwordx4 v[24:27], v[24:25], off
	s_nop 0
	global_load_dwordx4 v[68:71], v[2:3], off offset:3072
	global_load_dwordx4 v[72:75], v[2:3], off offset:2048
	global_load_dwordx4 v[76:79], v[2:3], off offset:1024
	global_load_dwordx4 v[80:83], v[2:3], off
	v_lshlrev_b32_e32 v1, 16, v8
	v_and_b32_e32 v2, 0xffff0000, v8
	v_mul_f32_e32 v1, 0x41000000, v1
	v_mul_f32_e32 v2, 0x41000000, v2
	v_mov_b32_e32 v150, v0
	v_cvt_pk_fp8_f32 v150, v1, v2
	v_lshlrev_b32_e32 v3, 16, v9
	v_and_b32_e32 v2, 0xffff0000, v9
	v_mul_f32_e32 v1, 0x41000000, v3
	v_mul_f32_e32 v2, 0x41000000, v2
	v_cvt_pk_fp8_f32 v150, v1, v2 op_sel:[0,0,1]
	v_lshlrev_b32_e32 v1, 16, v10
	v_and_b32_e32 v2, 0xffff0000, v10
	v_mul_f32_e32 v1, 0x41000000, v1
	v_mul_f32_e32 v2, 0x41000000, v2
	v_mov_b32_e32 v151, v0
	v_cvt_pk_fp8_f32 v151, v1, v2
	v_lshlrev_b32_e32 v3, 16, v11
	v_and_b32_e32 v2, 0xffff0000, v11
	v_mul_f32_e32 v1, 0x41000000, v3
	v_mul_f32_e32 v2, 0x41000000, v2
	v_cvt_pk_fp8_f32 v151, v1, v2 op_sel:[0,0,1]
	v_lshlrev_b32_e32 v1, 16, v4
	v_and_b32_e32 v2, 0xffff0000, v4
	v_mul_f32_e32 v1, 0x41000000, v1
	v_mul_f32_e32 v2, 0x41000000, v2
	v_mov_b32_e32 v10, v0
	v_cvt_pk_fp8_f32 v10, v1, v2
	v_max_i32_e32 v232, v154, v44
	v_lshlrev_b32_e32 v3, 16, v5
	v_and_b32_e32 v2, 0xffff0000, v5
	v_cvt_f32_u32_e32 v4, v232
	v_mul_f32_e32 v1, 0x41000000, v3
	v_mul_f32_e32 v2, 0x41000000, v2
	v_cvt_pk_fp8_f32 v10, v1, v2 op_sel:[0,0,1]
	v_lshlrev_b32_e32 v1, 16, v6
	v_and_b32_e32 v2, 0xffff0000, v6
	v_mul_f32_e32 v1, 0x41000000, v1
	v_mul_f32_e32 v2, 0x41000000, v2
	v_mov_b32_e32 v11, v0
	v_cvt_pk_fp8_f32 v11, v1, v2
	v_rcp_iflag_f32_e32 v1, v4
	v_lshlrev_b32_e32 v3, 16, v7
	v_and_b32_e32 v2, 0xffff0000, v7
	v_mul_f32_e32 v3, 0x41000000, v3
	v_mul_f32_e32 v1, 0x4f7ffffe, v1
	v_cvt_u32_f32_e32 v1, v1
	v_mul_f32_e32 v2, 0x41000000, v2
	v_cvt_pk_fp8_f32 v11, v3, v2 op_sel:[0,0,1]
	v_sub_u32_e32 v2, 0, v232
	v_mul_lo_u32 v2, v2, v1
	v_mul_hi_u32 v2, v1, v2
	v_add_u32_e32 v152, v1, v2
	v_mov_b32_e32 v2, v0
	v_mov_b32_e32 v3, v0
	v_mov_b32_e32 v1, v0
	v_mov_b64_e32 v[42:43], v[2:3]
	v_mov_b64_e32 v[38:39], v[2:3]
	v_mov_b64_e32 v[34:35], v[2:3]
	v_mov_b64_e32 v[30:31], v[2:3]
	v_cmp_eq_u32_e32 vcc, 0, v155
	v_ashrrev_i32_e32 v233, 31, v154
	s_mov_b32 s72, 0
	v_mov_b32_e32 v238, 0xf149f2ca
	v_mov_b32_e32 v241, 0
	s_mov_b64 s[18:19], 0
	v_mov_b64_e32 v[40:41], v[0:1]
	v_mov_b64_e32 v[36:37], v[0:1]
	v_mov_b64_e32 v[32:33], v[0:1]
	v_mov_b64_e32 v[28:29], v[0:1]
	s_branch .LBB0_578

.LBB0_578:
	s_add_i32 s24, s72, 1
	s_waitcnt vmcnt(24)
	s_cmp_gt_i32 s24, s37
	s_cselect_b32 s95, 1, 0
	s_min_i32 s93, s24, s37
	s_cmp_le_i32 s93, s32
	s_cbranch_scc0 .Lsel_pair_1
	s_sub_i32 s94, s75, 1
	s_cmp_eq_u32 s93, s32
	s_cselect_b32 s94, s75, s94
	s_mov_b32 s98, s94
	s_mov_b32 s100, -1
	s_branch .Lsel_done_1

.Lsel_done_1:
	v_mov_b32_e32 v240, s100
	s_nop 1
	v_mov_b32_e32 v1, s94
	v_mov_b32_e32 v239, s98
	v_lshlrev_b32_e32 v2, 12, v1
	s_waitcnt vmcnt(16)
	v_lshlrev_b32_e32 v100, 12, v239
	v_ashrrev_i32_e32 v3, 31, v2
	v_ashrrev_i32_e32 v101, 31, v100
	v_lshl_add_u64 v[4:5], v[200:201], 0, v[2:3]
	v_lshl_add_u64 v[2:3], v[198:199], 0, v[2:3]
	v_lshl_add_u64 v[102:103], v[200:201], 0, v[100:101]
	v_lshl_add_u64 v[100:101], v[198:199], 0, v[100:101]
	s_mov_b32 s99, 16
	s_cmp_lg_u32 s95, 0
	s_cbranch_scc0 .Lsk_a_1
	s_mov_b32 s99, 0
	s_branch .Lsk_end_1
.Lsk_a_1:
	global_load_dwordx4 v[128:131], v[4:5], off
	global_load_dwordx4 v[124:127], v[4:5], off offset:1024
	global_load_dwordx4 v[120:123], v[4:5], off offset:2048
	global_load_dwordx4 v[116:119], v[4:5], off offset:3072
	global_load_dwordx4 v[48:51], v[2:3], off
	global_load_dwordx4 v[44:47], v[2:3], off offset:1024
	global_load_dwordx4 v[6:9], v[2:3], off offset:2048
	s_nop 0
	global_load_dwordx4 v[2:5], v[2:3], off offset:3072
	s_nop 0
	s_cmp_lt_i32 s100, 0
	s_cbranch_scc0 .Lsk_b_1
	s_mov_b32 s99, 8
	s_branch .Lsk_end_1
.Lsk_b_1:
	global_load_dwordx4 v[144:147], v[102:103], off
	global_load_dwordx4 v[140:143], v[102:103], off offset:1024
	global_load_dwordx4 v[136:139], v[102:103], off offset:2048
	global_load_dwordx4 v[132:135], v[102:103], off offset:3072
	global_load_dwordx4 v[112:115], v[100:101], off
	global_load_dwordx4 v[108:111], v[100:101], off offset:1024
	global_load_dwordx4 v[104:107], v[100:101], off offset:2048
	s_nop 0
	global_load_dwordx4 v[100:103], v[100:101], off offset:3072
.Lsk_end_1:
	v_cmp_lt_i32_e64 s[0:1], -1, v236
	s_and_saveexec_b64 s[12:13], s[0:1]
	s_xor_b64 s[20:21], exec, s[12:13]
	s_cbranch_execz .LBB0_586
	v_lshlrev_b32_e32 v236, 1, v236
	v_cmp_ne_u32_e64 s[12:13], v208, v236
	v_cmp_ge_i32_e64 s[14:15], v234, v229
	v_cmp_eq_u32_e64 s[0:1], v208, v236
	s_or_b64 s[12:13], s[12:13], s[14:15]
	s_mov_b64 s[14:15], -1
	s_and_saveexec_b64 s[22:23], s[12:13]
	v_or_b32_e32 v234, 1, v236
	v_cmp_eq_u32_e64 s[12:13], v208, v234
	v_cmp_lt_i32_e64 s[14:15], v235, v229
	s_and_b64 s[12:13], s[12:13], s[14:15]
	s_orn2_b64 s[14:15], s[12:13], exec
	s_or_b64 exec, exec, s[22:23]
	v_cndmask_b32_e64 v243, 0, v151, s[0:1]
	v_cndmask_b32_e64 v242, 0, v150, s[0:1]
	v_cndmask_b32_e64 v245, 0, v11, s[0:1]
	v_cndmask_b32_e64 v244, 0, v10, s[0:1]
	s_cmp_eq_u32 s99, 16
	s_cbranch_scc1 .Lwkd_0
	s_cmp_eq_u32 s99, 8
	s_cbranch_scc1 .Lwk8_0
	s_waitcnt vmcnt(0)
	s_branch .Lwkd_0
.Lwk8_0:
	s_waitcnt vmcnt(8)
.Lwkd_0:
	s_waitcnt vmcnt(16)
	v_mfma_f32_16x16x32_fp8_fp8 v[234:237], v[80:81], v[242:243], 0
	s_and_b64 s[12:13], s[0:1], s[14:15]
	v_mfma_f32_16x16x32_fp8_fp8 v[80:83], v[82:83], v[244:245], v[234:237]
	s_nop 5
	v_cndmask_b32_e64 v235, v151, 0, s[0:1]
	v_cndmask_b32_e64 v234, v150, 0, s[0:1]
	v_cndmask_b32_e64 v237, v11, 0, s[0:1]
	v_cndmask_b32_e64 v236, v10, 0, s[0:1]
	v_mfma_f32_16x16x32_fp8_fp8 v[80:83], v[96:97], v[234:235], v[80:83]
	s_xor_b64 s[0:1], s[0:1], -1
	s_and_b64 s[0:1], s[14:15], s[0:1]
	v_mfma_f32_16x16x32_fp8_fp8 v[80:83], v[98:99], v[236:237], v[80:83]
	v_mfma_f32_16x16x32_fp8_fp8 v[96:99], v[76:77], v[242:243], 0
	v_mfma_f32_16x16x32_fp8_fp8 v[76:79], v[78:79], v[244:245], v[96:99]
	s_nop 5
	v_mfma_f32_16x16x32_fp8_fp8 v[76:79], v[92:93], v[234:235], v[76:79]
	v_mfma_f32_16x16x32_fp8_fp8 v[76:79], v[94:95], v[236:237], v[76:79]
	v_mfma_f32_16x16x32_fp8_fp8 v[92:95], v[72:73], v[242:243], 0
	v_mfma_f32_16x16x32_fp8_fp8 v[72:75], v[74:75], v[244:245], v[92:95]
	s_nop 5
	v_mfma_f32_16x16x32_fp8_fp8 v[72:75], v[88:89], v[234:235], v[72:75]
	v_mfma_f32_16x16x32_fp8_fp8 v[72:75], v[90:91], v[236:237], v[72:75]
	v_mfma_f32_16x16x32_fp8_fp8 v[88:91], v[68:69], v[242:243], 0
	v_mfma_f32_16x16x32_fp8_fp8 v[68:71], v[70:71], v[244:245], v[88:91]
	s_nop 5
	v_mfma_f32_16x16x32_fp8_fp8 v[68:71], v[84:85], v[234:235], v[68:71]
	v_max_f32_e32 v84, v80, v81
	v_max_f32_e32 v85, v82, v83
	v_mfma_f32_16x16x32_fp8_fp8 v[68:71], v[86:87], v[236:237], v[68:71]
	v_max_f32_e32 v86, v78, v79
	v_max3_f32 v86, v76, v77, v86
	v_max3_f32 v84, v84, v85, v86
	v_max_f32_e32 v85, v74, v75
	v_max3_f32 v85, v72, v73, v85
	s_nop 2
	v_max_f32_e32 v86, v70, v71
	v_max3_f32 v86, v68, v69, v86
	v_max3_f32 v84, v84, v85, v86
	v_mov_b32_e32 v85, v84
	s_nop 1
	v_permlane16_swap_b32_e32 v84, v85
	v_max_f32_e32 v84, v84, v85
	v_mov_b32_e32 v85, v84
	s_nop 1
	v_permlane32_swap_b32_e32 v84, v85
	v_max_f32_e32 v84, v84, v85
	v_mul_f32_e64 v84, v84, s76
	v_max_f32_e32 v84, v238, v84
	v_cndmask_b32_e64 v85, v238, v84, s[14:15]
	v_sub_f32_e32 v88, 0x41000000, v85
	v_fma_f32 v80, v80, s76, v88
	v_fma_f32 v81, v81, s76, v88
	v_fma_f32 v76, v76, s76, v88
	v_fma_f32 v77, v77, s76, v88
	v_exp_f32_e32 v80, v80
	v_exp_f32_e32 v81, v81
	v_exp_f32_e32 v76, v76
	v_exp_f32_e32 v77, v77
	v_fma_f32 v82, v82, s76, v88
	v_fma_f32 v83, v83, s76, v88
	v_fma_f32 v78, v78, s76, v88
	v_fma_f32 v79, v79, s76, v88
	v_exp_f32_e32 v82, v82
	v_exp_f32_e32 v83, v83
	v_exp_f32_e32 v78, v78
	v_exp_f32_e32 v79, v79
	v_cvt_pk_fp8_f32 v90, v76, v77
	v_cvt_pk_fp8_f32 v89, v80, v81
	v_sub_f32_e32 v84, v238, v85
	v_exp_f32_e32 v84, v84
	v_cvt_pk_fp8_f32 v90, v78, v79 op_sel:[0,0,1]
	v_cvt_pk_fp8_f32 v89, v82, v83 op_sel:[0,0,1]
	v_fma_f32 v72, v72, s76, v88
	v_pk_mul_f32 v[42:43], v[42:43], v[84:85] op_sel_hi:[1,0]
	v_pk_mul_f32 v[40:41], v[40:41], v[84:85] op_sel_hi:[1,0]
	v_cndmask_b32_e64 v87, 0, v90, s[12:13]
	v_cndmask_b32_e64 v86, 0, v89, s[12:13]
	v_pk_mul_f32 v[38:39], v[38:39], v[84:85] op_sel_hi:[1,0]
	v_pk_mul_f32 v[36:37], v[36:37], v[84:85] op_sel_hi:[1,0]
	v_pk_mul_f32 v[34:35], v[34:35], v[84:85] op_sel_hi:[1,0]
	v_pk_mul_f32 v[32:33], v[32:33], v[84:85] op_sel_hi:[1,0]
	v_fma_f32 v73, v73, s76, v88
	v_mfma_f32_16x16x32_fp8_fp8 v[40:43], v[24:25], v[86:87], v[40:43]
	v_fma_f32 v24, v68, s76, v88
	v_exp_f32_e32 v72, v72
	v_exp_f32_e32 v73, v73
	v_mfma_f32_16x16x32_fp8_fp8 v[36:39], v[20:21], v[86:87], v[36:39]
	v_exp_f32_e32 v68, v24
	v_pk_mul_f32 v[30:31], v[30:31], v[84:85] op_sel_hi:[1,0]
	v_pk_mul_f32 v[28:29], v[28:29], v[84:85] op_sel_hi:[1,0]
	v_mfma_f32_16x16x32_fp8_fp8 v[32:35], v[16:17], v[86:87], v[32:35]
	v_fma_f32 v16, v69, s76, v88
	v_exp_f32_e32 v69, v16
	v_fma_f32 v16, v70, s76, v88
	v_mfma_f32_16x16x32_fp8_fp8 v[28:31], v[12:13], v[86:87], v[28:31]
	v_cndmask_b32_e64 v13, 0, v90, s[0:1]
	v_cndmask_b32_e64 v12, 0, v89, s[0:1]
	v_fma_f32 v74, v74, s76, v88
	v_fma_f32 v75, v75, s76, v88
	v_mfma_f32_16x16x32_fp8_fp8 v[36:39], v[60:61], v[12:13], v[36:39]
	v_exp_f32_e32 v60, v16
	v_fma_f32 v16, v71, s76, v88
	v_exp_f32_e32 v74, v74
	v_mfma_f32_16x16x32_fp8_fp8 v[32:35], v[56:57], v[12:13], v[32:35]
	v_exp_f32_e32 v75, v75
	v_exp_f32_e32 v61, v16
	v_cvt_pk_fp8_f32 v57, v68, v69
	v_cvt_pk_fp8_f32 v56, v72, v73
	v_mfma_f32_16x16x32_fp8_fp8 v[40:43], v[64:65], v[12:13], v[40:43]
	v_mov_b32_e32 v238, v85
	v_cvt_pk_fp8_f32 v57, v60, v61 op_sel:[0,0,1]
	v_cvt_pk_fp8_f32 v56, v74, v75 op_sel:[0,0,1]
	v_mfma_f32_16x16x32_fp8_fp8 v[28:31], v[52:53], v[12:13], v[28:31]
	v_cndmask_b32_e64 v13, 0, v57, s[12:13]
	v_cndmask_b32_e64 v12, 0, v56, s[12:13]
	s_nop 1
	v_mfma_f32_16x16x32_fp8_fp8 v[24:27], v[26:27], v[12:13], v[40:43]
	v_mfma_f32_16x16x32_fp8_fp8 v[20:23], v[22:23], v[12:13], v[36:39]
	s_nop 2
	v_mfma_f32_16x16x32_fp8_fp8 v[16:19], v[18:19], v[12:13], v[32:35]
	s_nop 2
	v_pk_add_f32 v[34:35], v[76:77], v[80:81]
	v_pk_add_f32 v[32:33], v[78:79], v[82:83]
	v_mfma_f32_16x16x32_fp8_fp8 v[12:15], v[14:15], v[12:13], v[28:31]
	s_nop 2
	v_cndmask_b32_e64 v31, 0, v57, s[0:1]
	v_cndmask_b32_e64 v30, 0, v56, s[0:1]
	v_pk_add_f32 v[28:29], v[72:73], v[34:35]
	s_nop 0
	v_mfma_f32_16x16x32_fp8_fp8 v[40:43], v[66:67], v[30:31], v[24:27]
	s_nop 2
	v_add_f32_e64 v24, v74, v32
	v_add_f32_e64 v25, v75, v33
	v_pk_add_f32 v[26:27], v[68:69], v[28:29]
	v_pk_add_f32 v[24:25], v[60:61], v[24:25]
	v_mfma_f32_16x16x32_fp8_fp8 v[36:39], v[62:63], v[30:31], v[20:23]
	v_mfma_f32_16x16x32_fp8_fp8 v[32:35], v[58:59], v[30:31], v[16:19]
	s_nop 1
	v_pk_mov_b32 v[20:21], v[26:27], v[24:25] op_sel:[1,0]
	v_mov_b32_e32 v27, v25
	v_pk_add_f32 v[20:21], v[20:21], v[26:27]
	v_mfma_f32_16x16x32_fp8_fp8 v[28:31], v[54:55], v[30:31], v[12:15]
	v_add_f32_e32 v16, v20, v21
	v_cndmask_b32_e64 v237, 0, v16, s[14:15]
	v_fmac_f32_e32 v237, v241, v84
.LBB0_586:
	s_andn2_saveexec_b64 s[12:13], s[20:21]
	s_cbranch_execz .LBB0_592
	v_cmp_ge_i32_e64 s[0:1], v234, v229
	s_and_saveexec_b64 s[14:15], s[0:1]
	s_xor_b64 s[14:15], exec, s[14:15]
	s_cbranch_execz .LBB0_589
	s_cmp_eq_u32 s99, 16
	s_cbranch_scc1 .Lwkd_1
	s_cmp_eq_u32 s99, 8
	s_cbranch_scc1 .Lwk8_1
	s_waitcnt vmcnt(0)
	s_branch .Lwkd_1

.Lwkd_1:
	s_waitcnt vmcnt(16)
	v_mfma_f32_16x16x32_fp8_fp8 v[52:55], v[80:81], v[150:151], 0
	v_mfma_f32_16x16x32_fp8_fp8 v[52:55], v[82:83], v[10:11], v[52:55]
	v_mfma_f32_16x16x32_fp8_fp8 v[56:59], v[76:77], v[150:151], 0
	v_mfma_f32_16x16x32_fp8_fp8 v[56:59], v[78:79], v[10:11], v[56:59]
	s_nop 5
	v_mul_f32_e64 v64, v54, s76
	v_mul_f32_e64 v65, v55, s76
	v_pk_mul_f32 v[66:67], v[52:53], s[76:77] op_sel_hi:[1,0]
	v_mfma_f32_16x16x32_fp8_fp8 v[52:55], v[68:69], v[150:151], 0
	v_lshl_or_b32 v68, v234, 6, v212
	v_cmp_le_i32_e64 s[0:1], v68, v228
	v_or_b32_e32 v69, 2, v68
	v_mfma_f32_16x16x32_fp8_fp8 v[60:63], v[72:73], v[150:151], 0
	v_cndmask_b32_e64 v66, v220, v66, s[0:1]
	v_cmp_lt_i32_e64 s[0:1], v68, v228
	v_pk_mul_f32 v[56:57], v[56:57], s[76:77] op_sel_hi:[1,0]
	v_mfma_f32_16x16x32_fp8_fp8 v[60:63], v[74:75], v[10:11], v[60:63]
	v_cndmask_b32_e64 v67, v220, v67, s[0:1]
	v_cmp_le_i32_e64 s[0:1], v69, v228
	v_or_b32_e32 v69, 3, v68
	v_pk_mul_f32 v[58:59], v[58:59], s[76:77] op_sel_hi:[1,0]
	v_cndmask_b32_e64 v64, v220, v64, s[0:1]
	v_cmp_le_i32_e64 s[0:1], v69, v228
	v_or_b32_e32 v69, 16, v68
	v_mfma_f32_16x16x32_fp8_fp8 v[52:55], v[70:71], v[10:11], v[52:55]
	v_cndmask_b32_e64 v65, v220, v65, s[0:1]
	v_cmp_le_i32_e64 s[0:1], v69, v228
	v_pk_mul_f32 v[60:61], v[60:61], s[76:77] op_sel_hi:[1,0]
	v_pk_mul_f32 v[62:63], v[62:63], s[76:77] op_sel_hi:[1,0]
	v_cndmask_b32_e64 v69, v220, v56, s[0:1]
	v_or_b32_e32 v56, 17, v68
	v_cmp_le_i32_e64 s[0:1], v56, v228
	v_or_b32_e32 v56, 18, v68
	v_pk_mul_f32 v[52:53], v[52:53], s[76:77] op_sel_hi:[1,0]
	v_cndmask_b32_e64 v70, v220, v57, s[0:1]
	v_cmp_le_i32_e64 s[0:1], v56, v228
	v_or_b32_e32 v56, 19, v68
	v_pk_mul_f32 v[54:55], v[54:55], s[76:77] op_sel_hi:[1,0]
	v_cndmask_b32_e64 v71, v220, v58, s[0:1]
	v_cmp_le_i32_e64 s[0:1], v56, v228
	v_or_b32_e32 v56, 32, v68
	s_nop 0
	v_cndmask_b32_e64 v72, v220, v59, s[0:1]
	v_cmp_le_i32_e64 s[0:1], v56, v228
	v_or_b32_e32 v56, 33, v68
	s_nop 0
	v_cndmask_b32_e64 v73, v220, v60, s[0:1]
	v_cmp_le_i32_e64 s[0:1], v56, v228
	v_or_b32_e32 v56, 34, v68
	s_nop 0
	v_cndmask_b32_e64 v74, v220, v61, s[0:1]
	v_cmp_le_i32_e64 s[0:1], v56, v228
	v_or_b32_e32 v56, 35, v68
	s_nop 0
	v_cndmask_b32_e64 v75, v220, v62, s[0:1]
	v_cmp_le_i32_e64 s[0:1], v56, v228
	v_or_b32_e32 v56, 48, v68
	s_nop 0
	v_cndmask_b32_e64 v76, v220, v63, s[0:1]
	v_cmp_le_i32_e64 s[0:1], v56, v228
	s_nop 1
	v_cndmask_b32_e64 v77, v220, v52, s[0:1]
	v_or_b32_e32 v52, 49, v68
	v_cmp_le_i32_e64 s[0:1], v52, v228
	v_or_b32_e32 v52, 50, v68
	s_nop 0
	v_cndmask_b32_e64 v78, v220, v53, s[0:1]
	v_cmp_le_i32_e64 s[0:1], v52, v228
	v_or_b32_e32 v52, 51, v68
	v_max_f32_e32 v53, v64, v65
	v_cndmask_b32_e64 v79, v220, v54, s[0:1]
	v_cmp_le_i32_e64 s[0:1], v52, v228
	v_max_f32_e32 v54, v71, v72
	v_max_f32_e32 v52, v66, v67
	v_cndmask_b32_e64 v80, v220, v55, s[0:1]
	v_max3_f32 v54, v69, v70, v54
	v_max3_f32 v52, v52, v53, v54
	v_max_f32_e32 v53, v75, v76
	v_max_f32_e32 v54, v79, v80
	v_max3_f32 v53, v73, v74, v53
	v_max3_f32 v54, v77, v78, v54
	v_max3_f32 v52, v52, v53, v54
	v_mov_b32_e32 v53, v52
	v_cmp_lt_f32_e64 s[0:1], s83, v66
	s_nop 1
	v_permlane16_swap_b32_e32 v52, v53
	v_max_f32_e32 v52, v52, v53
	v_mov_b32_e32 v53, v52
	s_nop 1
	v_permlane32_swap_b32_e32 v52, v53
	v_max3_f32 v81, v238, v52, v53
	v_sub_f32_e32 v82, 0x41000000, v81
	v_add_f32_e32 v52, v66, v82
	v_exp_f32_e32 v52, v52
	v_add_f32_e32 v53, v67, v82
	v_exp_f32_e32 v53, v53
	v_add_f32_e32 v54, v64, v82
	v_exp_f32_e32 v54, v54
	v_add_f32_e32 v55, v65, v82
	v_exp_f32_e32 v55, v55
	v_add_f32_e32 v56, v69, v82
	v_cndmask_b32_e64 v52, 0, v52, s[0:1]
	v_cmp_lt_f32_e64 s[0:1], s83, v67
	v_exp_f32_e32 v58, v56
	v_add_f32_e32 v59, v70, v82
	v_cndmask_b32_e64 v53, 0, v53, s[0:1]
	v_cmp_lt_f32_e64 s[0:1], s83, v64
	v_exp_f32_e32 v59, v59
	v_add_f32_e32 v60, v71, v82
	v_cndmask_b32_e64 v54, 0, v54, s[0:1]
	v_cmp_lt_f32_e64 s[0:1], s83, v65
	v_exp_f32_e32 v60, v60
	v_add_f32_e32 v61, v72, v82
	v_cndmask_b32_e64 v55, 0, v55, s[0:1]
	v_cmp_lt_f32_e64 s[0:1], s83, v69
	v_exp_f32_e32 v61, v61
	v_add_f32_e32 v62, v73, v82
	v_cndmask_b32_e64 v58, 0, v58, s[0:1]
	v_cmp_lt_f32_e64 s[0:1], s83, v70
	v_exp_f32_e32 v62, v62
	v_add_f32_e32 v63, v74, v82
	v_cndmask_b32_e64 v59, 0, v59, s[0:1]
	v_cmp_lt_f32_e64 s[0:1], s83, v71
	v_mov_b32_e32 v70, 0
	v_mov_b32_e32 v71, 0
	v_exp_f32_e32 v63, v63
	v_add_f32_e32 v64, v75, v82
	v_cvt_pk_fp8_f32 v70, v52, v53
	v_cvt_pk_fp8_f32 v71, v58, v59
	v_cndmask_b32_e64 v60, 0, v60, s[0:1]
	v_cmp_lt_f32_e64 s[0:1], s83, v72
	v_exp_f32_e32 v64, v64
	v_add_f32_e32 v65, v76, v82
	v_sub_f32_e32 v83, v238, v81
	v_pk_add_f32 v[56:57], v[52:53], 0 op_sel_hi:[1,0]
	v_cndmask_b32_e64 v61, 0, v61, s[0:1]
	v_cmp_lt_f32_e64 s[0:1], s83, v73
	v_exp_f32_e32 v65, v65
	v_add_f32_e32 v66, v77, v82
	v_add_f32_e32 v53, v80, v82
	v_cndmask_b32_e64 v62, 0, v62, s[0:1]
	v_cmp_lt_f32_e64 s[0:1], s83, v74
	v_exp_f32_e32 v66, v66
	v_add_f32_e32 v67, v78, v82
	v_exp_f32_e32 v52, v83
	v_exp_f32_e32 v53, v53
	v_cndmask_b32_e64 v63, 0, v63, s[0:1]
	v_cmp_lt_f32_e64 s[0:1], s83, v75
	v_exp_f32_e32 v67, v67
	v_cvt_pk_fp8_f32 v70, v54, v55 op_sel:[0,0,1]
	v_cvt_pk_fp8_f32 v71, v60, v61 op_sel:[0,0,1]
	v_cndmask_b32_e64 v64, 0, v64, s[0:1]
	v_cmp_lt_f32_e64 s[0:1], s83, v76
	v_add_f32_e32 v68, v79, v82
	v_exp_f32_e32 v68, v68
	v_cndmask_b32_e64 v65, 0, v65, s[0:1]
	v_cmp_lt_f32_e64 s[0:1], s83, v77
	v_pk_mul_f32 v[34:35], v[34:35], v[52:53] op_sel_hi:[1,0]
	v_pk_mul_f32 v[32:33], v[32:33], v[52:53] op_sel_hi:[1,0]
	v_cndmask_b32_e64 v66, 0, v66, s[0:1]
	v_cmp_lt_f32_e64 s[0:1], s83, v78
	v_mfma_f32_16x16x32_fp8_fp8 v[32:35], v[16:17], v[70:71], v[32:35]
	v_mov_b32_e32 v16, 0
	v_cndmask_b32_e64 v67, 0, v67, s[0:1]
	v_mov_b32_e32 v17, 0
	v_cvt_pk_fp8_f32 v16, v62, v63
	v_cvt_pk_fp8_f32 v17, v66, v67
	v_cmp_lt_f32_e64 s[0:1], s83, v79
	v_pk_mul_f32 v[38:39], v[38:39], v[52:53] op_sel_hi:[1,0]
	v_pk_mul_f32 v[36:37], v[36:37], v[52:53] op_sel_hi:[1,0]
	v_cndmask_b32_e64 v68, 0, v68, s[0:1]
	v_cmp_lt_f32_e64 s[0:1], s83, v80
	v_pk_mul_f32 v[30:31], v[30:31], v[52:53] op_sel_hi:[1,0]
	v_pk_mul_f32 v[28:29], v[28:29], v[52:53] op_sel_hi:[1,0]
	v_cndmask_b32_e64 v69, 0, v53, s[0:1]
	v_mfma_f32_16x16x32_fp8_fp8 v[36:39], v[20:21], v[70:71], v[36:39]
	v_cvt_pk_fp8_f32 v16, v64, v65 op_sel:[0,0,1]
	v_cvt_pk_fp8_f32 v17, v68, v69 op_sel:[0,0,1]
	v_pk_add_f32 v[20:21], v[58:59], v[56:57]
	v_mfma_f32_16x16x32_fp8_fp8 v[28:31], v[12:13], v[70:71], v[28:31]
	v_add_f32_e64 v12, v54, 0
	v_add_f32_e64 v13, v55, 0
	v_pk_mul_f32 v[42:43], v[42:43], v[52:53] op_sel_hi:[1,0]
	v_pk_add_f32 v[12:13], v[60:61], v[12:13]
	v_pk_mul_f32 v[40:41], v[40:41], v[52:53] op_sel_hi:[1,0]
	v_pk_add_f32 v[20:21], v[62:63], v[20:21]
	v_pk_add_f32 v[12:13], v[64:65], v[12:13]
	v_mfma_f32_16x16x32_fp8_fp8 v[40:43], v[24:25], v[70:71], v[40:43]
	v_add_f32_e64 v12, v68, v12
	v_add_f32_e64 v13, v69, v13
	v_pk_add_f32 v[20:21], v[66:67], v[20:21]
	v_mov_b32_e32 v238, v81
	v_mfma_f32_16x16x32_fp8_fp8 v[36:39], v[22:23], v[16:17], v[36:39]
	v_pk_mov_b32 v[22:23], v[20:21], v[12:13] op_sel:[1,0]
	v_mov_b32_e32 v21, v13
	v_pk_add_f32 v[12:13], v[22:23], v[20:21]
	v_mfma_f32_16x16x32_fp8_fp8 v[40:43], v[26:27], v[16:17], v[40:43]
	v_add_f32_e32 v237, v12, v13
	v_fmac_f32_e32 v237, v241, v52
	v_mfma_f32_16x16x32_fp8_fp8 v[32:35], v[18:19], v[16:17], v[32:35]
	v_mfma_f32_16x16x32_fp8_fp8 v[28:31], v[14:15], v[16:17], v[28:31]
.LBB0_589:
	s_andn2_saveexec_b64 s[0:1], s[14:15]
	s_cbranch_execz .LBB0_591
	s_cmp_eq_u32 s99, 16
	s_cbranch_scc1 .Lwkd_2
	s_cmp_eq_u32 s99, 8
	s_cbranch_scc1 .Lwk8_2
	s_waitcnt vmcnt(0)
	s_branch .Lwkd_2

.Lwkd_2:
	s_waitcnt vmcnt(16)
	v_mfma_f32_16x16x32_fp8_fp8 v[52:55], v[80:81], v[150:151], 0
	v_mfma_f32_16x16x32_fp8_fp8 v[52:55], v[82:83], v[10:11], v[52:55]
	v_mfma_f32_16x16x32_fp8_fp8 v[56:59], v[76:77], v[150:151], 0
	v_mfma_f32_16x16x32_fp8_fp8 v[60:63], v[72:73], v[150:151], 0
	s_nop 5
	v_mul_f32_e64 v64, v54, s76
	v_mul_f32_e64 v65, v55, s76
	v_pk_mul_f32 v[66:67], v[52:53], s[76:77] op_sel_hi:[1,0]
	v_mfma_f32_16x16x32_fp8_fp8 v[52:55], v[68:69], v[150:151], 0
	v_max_f32_e32 v68, v66, v67
	v_max_f32_e32 v69, v64, v65
	v_mfma_f32_16x16x32_fp8_fp8 v[56:59], v[78:79], v[10:11], v[56:59]
	v_mfma_f32_16x16x32_fp8_fp8 v[60:63], v[74:75], v[10:11], v[60:63]
	v_mfma_f32_16x16x32_fp8_fp8 v[52:55], v[70:71], v[10:11], v[52:55]
	s_nop 5
	v_mul_f32_e64 v58, v58, s76
	v_mul_f32_e64 v59, v59, s76
	v_pk_mul_f32 v[56:57], v[56:57], s[76:77] op_sel_hi:[1,0]
	v_max_f32_e32 v70, v58, v59
	v_pk_mul_f32 v[62:63], v[62:63], s[76:77] op_sel_hi:[1,0]
	v_max3_f32 v70, v56, v57, v70
	v_pk_mul_f32 v[54:55], v[54:55], s[76:77] op_sel_hi:[1,0]
	v_pk_mul_f32 v[60:61], v[60:61], s[76:77] op_sel_hi:[1,0]
	v_pk_mul_f32 v[52:53], v[52:53], s[76:77] op_sel_hi:[1,0]
	v_max3_f32 v68, v68, v69, v70
	v_max_f32_e32 v69, v62, v63
	v_max_f32_e32 v70, v54, v55
	v_max3_f32 v69, v60, v61, v69
	v_max3_f32 v70, v52, v53, v70
	v_max3_f32 v68, v68, v69, v70
	v_mov_b32_e32 v69, v68
	v_mov_b32_e32 v70, 0
	v_mov_b32_e32 v71, 0
	s_nop 1
	v_permlane16_swap_b32_e32 v68, v69
	v_max_f32_e32 v68, v68, v69
	v_mov_b32_e32 v69, v68
	s_nop 1
	v_permlane32_swap_b32_e32 v68, v69
	v_max3_f32 v72, v238, v68, v69
	v_sub_f32_e32 v74, 0x41000000, v72
	v_add_f32_e32 v66, v66, v74
	v_add_f32_e32 v67, v67, v74
	v_add_f32_e32 v56, v56, v74
	v_add_f32_e32 v57, v57, v74
	v_exp_f32_e32 v66, v66
	v_exp_f32_e32 v67, v67
	v_exp_f32_e32 v56, v56
	v_exp_f32_e32 v57, v57
	v_add_f32_e32 v64, v64, v74
	v_add_f32_e32 v65, v65, v74
	v_add_f32_e32 v58, v58, v74
	v_add_f32_e32 v59, v59, v74
	v_exp_f32_e32 v64, v64
	v_exp_f32_e32 v65, v65
	v_exp_f32_e32 v58, v58
	v_exp_f32_e32 v59, v59
	v_cvt_pk_fp8_f32 v70, v66, v67
	v_cvt_pk_fp8_f32 v71, v56, v57
	v_sub_f32_e32 v73, v238, v72
	v_pk_add_f32 v[68:69], v[66:67], 0 op_sel_hi:[1,0]
	v_exp_f32_e32 v66, v73
	v_add_f32_e32 v60, v60, v74
	v_add_f32_e32 v61, v61, v74
	v_add_f32_e32 v52, v52, v74
	v_add_f32_e32 v53, v53, v74
	v_cvt_pk_fp8_f32 v70, v64, v65 op_sel:[0,0,1]
	v_cvt_pk_fp8_f32 v71, v58, v59 op_sel:[0,0,1]
	v_exp_f32_e32 v60, v60
	v_exp_f32_e32 v61, v61
	v_exp_f32_e32 v52, v52
	v_exp_f32_e32 v53, v53
	v_pk_mul_f32 v[34:35], v[34:35], v[66:67] op_sel_hi:[1,0]
	v_pk_mul_f32 v[32:33], v[32:33], v[66:67] op_sel_hi:[1,0]
	v_add_f32_e32 v62, v62, v74
	v_add_f32_e32 v63, v63, v74
	v_add_f32_e32 v54, v54, v74
	v_add_f32_e32 v55, v55, v74
	v_mfma_f32_16x16x32_fp8_fp8 v[32:35], v[16:17], v[70:71], v[32:35]
	v_mov_b32_e32 v16, 0
	v_mov_b32_e32 v17, 0
	v_exp_f32_e32 v62, v62
	v_exp_f32_e32 v63, v63
	v_exp_f32_e32 v54, v54
	v_exp_f32_e32 v55, v55
	v_cvt_pk_fp8_f32 v16, v60, v61
	v_cvt_pk_fp8_f32 v17, v52, v53
	v_pk_mul_f32 v[42:43], v[42:43], v[66:67] op_sel_hi:[1,0]
	v_pk_mul_f32 v[40:41], v[40:41], v[66:67] op_sel_hi:[1,0]
	v_pk_mul_f32 v[38:39], v[38:39], v[66:67] op_sel_hi:[1,0]
	v_pk_mul_f32 v[36:37], v[36:37], v[66:67] op_sel_hi:[1,0]
	v_pk_mul_f32 v[30:31], v[30:31], v[66:67] op_sel_hi:[1,0]
	v_pk_mul_f32 v[28:29], v[28:29], v[66:67] op_sel_hi:[1,0]
	v_mfma_f32_16x16x32_fp8_fp8 v[40:43], v[24:25], v[70:71], v[40:43]
	v_cvt_pk_fp8_f32 v16, v62, v63 op_sel:[0,0,1]
	v_cvt_pk_fp8_f32 v17, v54, v55 op_sel:[0,0,1]
	v_mov_b32_e32 v238, v72
	v_mfma_f32_16x16x32_fp8_fp8 v[36:39], v[20:21], v[70:71], v[36:39]
	v_add_f32_e64 v20, v56, v68
	v_add_f32_e64 v21, v57, v69
	v_pk_add_f32 v[20:21], v[60:61], v[20:21]
	v_mfma_f32_16x16x32_fp8_fp8 v[28:31], v[12:13], v[70:71], v[28:31]
	v_add_f32_e64 v12, v64, 0
	v_add_f32_e64 v13, v65, 0
	v_pk_add_f32 v[20:21], v[52:53], v[20:21]
	v_pk_add_f32 v[12:13], v[58:59], v[12:13]
	v_mfma_f32_16x16x32_fp8_fp8 v[40:43], v[26:27], v[16:17], v[40:43]
	v_add_f32_e64 v12, v62, v12
	v_add_f32_e64 v13, v63, v13
	v_pk_add_f32 v[12:13], v[54:55], v[12:13]
	v_mfma_f32_16x16x32_fp8_fp8 v[36:39], v[22:23], v[16:17], v[36:39]
	v_pk_mov_b32 v[22:23], v[20:21], v[12:13] op_sel:[1,0]
	v_mov_b32_e32 v21, v13
	v_pk_add_f32 v[12:13], v[22:23], v[20:21]
	v_mfma_f32_16x16x32_fp8_fp8 v[32:35], v[18:19], v[16:17], v[32:35]
	v_add_f32_e32 v237, v12, v13
	v_fmac_f32_e32 v237, v241, v66
	v_mfma_f32_16x16x32_fp8_fp8 v[28:31], v[14:15], v[16:17], v[28:31]

.LBB0_592:
	s_or_b64 exec, exec, s[12:13]
	s_add_i32 s72, s72, 2
	s_waitcnt vmcnt(23)
	s_cmp_gt_i32 s72, s37
	s_cselect_b32 s95, 1, 0
	s_min_i32 s93, s72, s37
	s_cmp_le_i32 s93, s32
	s_cbranch_scc0 .Lsel_pair_2
	s_sub_i32 s94, s75, 1
	s_cmp_eq_u32 s93, s32
	s_cselect_b32 s94, s75, s94
	s_mov_b32 s98, s94
	s_mov_b32 s100, -1
	s_branch .Lsel_done_2

.Lsel_done_2:
	v_mov_b32_e32 v236, s100
	s_nop 1
	v_mov_b32_e32 v234, s94
	v_mov_b32_e32 v235, s98
	v_lshlrev_b32_e32 v12, 12, v234
	s_waitcnt vmcnt(16)
	v_lshlrev_b32_e32 v52, 12, v235
	v_ashrrev_i32_e32 v13, 31, v12
	v_ashrrev_i32_e32 v53, 31, v52
	v_lshl_add_u64 v[14:15], v[200:201], 0, v[12:13]
	v_lshl_add_u64 v[12:13], v[198:199], 0, v[12:13]
	v_lshl_add_u64 v[54:55], v[200:201], 0, v[52:53]
	v_lshl_add_u64 v[52:53], v[198:199], 0, v[52:53]
	s_mov_b32 s99, 16
	s_cmp_lg_u32 s95, 0
	s_cbranch_scc0 .Lsk_a_2
	s_mov_b32 s99, 0
	s_branch .Lsk_end_2
.Lsk_a_2:
	global_load_dwordx4 v[80:83], v[14:15], off
	global_load_dwordx4 v[76:79], v[14:15], off offset:1024
	global_load_dwordx4 v[72:75], v[14:15], off offset:2048
	global_load_dwordx4 v[68:71], v[14:15], off offset:3072
	global_load_dwordx4 v[24:27], v[12:13], off
	global_load_dwordx4 v[20:23], v[12:13], off offset:1024
	global_load_dwordx4 v[16:19], v[12:13], off offset:2048
	s_nop 0
	global_load_dwordx4 v[12:15], v[12:13], off offset:3072
	s_nop 0
	s_cmp_lt_i32 s100, 0
	s_cbranch_scc0 .Lsk_b_2
	s_mov_b32 s99, 8
	s_branch .Lsk_end_2
.Lsk_b_2:
	global_load_dwordx4 v[96:99], v[54:55], off
	global_load_dwordx4 v[92:95], v[54:55], off offset:1024
	global_load_dwordx4 v[88:91], v[54:55], off offset:2048
	global_load_dwordx4 v[84:87], v[54:55], off offset:3072
	global_load_dwordx4 v[64:67], v[52:53], off
	global_load_dwordx4 v[60:63], v[52:53], off offset:1024
	global_load_dwordx4 v[56:59], v[52:53], off offset:2048
	s_nop 0
	global_load_dwordx4 v[52:55], v[52:53], off offset:3072
.Lsk_end_2:
	v_cmp_lt_u32_e64 s[0:1], s24, v231
	s_and_saveexec_b64 s[20:21], s[0:1]
	s_cbranch_execz .LBB0_577
	v_cmp_lt_i32_e64 s[0:1], -1, v240
	s_and_saveexec_b64 s[12:13], s[0:1]
	s_xor_b64 s[22:23], exec, s[12:13]
	s_cbranch_execz .LBB0_601
	v_lshlrev_b32_e32 v240, 1, v240
	v_cmp_ne_u32_e64 s[12:13], v208, v240
	v_cmp_ge_i32_e64 s[14:15], v1, v229
	v_cmp_eq_u32_e64 s[0:1], v208, v240
	s_or_b64 s[12:13], s[12:13], s[14:15]
	s_mov_b64 s[14:15], -1
	s_and_saveexec_b64 s[24:25], s[12:13]
	v_or_b32_e32 v1, 1, v240
	v_cmp_eq_u32_e64 s[12:13], v208, v1
	v_cmp_lt_i32_e64 s[14:15], v239, v229
	s_and_b64 s[12:13], s[12:13], s[14:15]
	s_orn2_b64 s[14:15], s[12:13], exec
	s_or_b64 exec, exec, s[24:25]
	v_cndmask_b32_e64 v245, 0, v151, s[0:1]
	v_cndmask_b32_e64 v244, 0, v150, s[0:1]
	v_cndmask_b32_e64 v247, 0, v11, s[0:1]
	v_cndmask_b32_e64 v246, 0, v10, s[0:1]
	s_cmp_eq_u32 s99, 16
	s_cbranch_scc1 .Lwkd_3
	s_cmp_eq_u32 s99, 8
	s_cbranch_scc1 .Lwk8_3
	s_waitcnt vmcnt(0)
	s_branch .Lwkd_3

.Lwkd_3:
	s_waitcnt vmcnt(31)
	v_mfma_f32_16x16x32_fp8_fp8 v[240:243], v[128:129], v[244:245], 0
	s_and_b64 s[12:13], s[0:1], s[14:15]
	v_mfma_f32_16x16x32_fp8_fp8 v[128:131], v[130:131], v[246:247], v[240:243]
	s_nop 5
	v_cndmask_b32_e64 v241, v151, 0, s[0:1]
	v_cndmask_b32_e64 v240, v150, 0, s[0:1]
	v_cndmask_b32_e64 v243, v11, 0, s[0:1]
	v_cndmask_b32_e64 v242, v10, 0, s[0:1]
	s_waitcnt vmcnt(23)
	v_mfma_f32_16x16x32_fp8_fp8 v[128:131], v[144:145], v[240:241], v[128:131]
	s_xor_b64 s[0:1], s[0:1], -1
	s_and_b64 s[0:1], s[14:15], s[0:1]
	v_mfma_f32_16x16x32_fp8_fp8 v[128:131], v[146:147], v[242:243], v[128:131]
	v_mfma_f32_16x16x32_fp8_fp8 v[144:147], v[124:125], v[244:245], 0
	v_mfma_f32_16x16x32_fp8_fp8 v[124:127], v[126:127], v[246:247], v[144:147]
	s_nop 5
	s_waitcnt vmcnt(22)
	v_mfma_f32_16x16x32_fp8_fp8 v[124:127], v[140:141], v[240:241], v[124:127]
	v_max_f32_e32 v1, v128, v129
	v_mfma_f32_16x16x32_fp8_fp8 v[124:127], v[142:143], v[242:243], v[124:127]
	v_mfma_f32_16x16x32_fp8_fp8 v[140:143], v[120:121], v[244:245], 0
	v_mfma_f32_16x16x32_fp8_fp8 v[120:123], v[122:123], v[246:247], v[140:143]
	s_nop 5
	s_waitcnt vmcnt(21)
	v_mfma_f32_16x16x32_fp8_fp8 v[120:123], v[136:137], v[240:241], v[120:123]
	v_mfma_f32_16x16x32_fp8_fp8 v[120:123], v[138:139], v[242:243], v[120:123]
	v_mfma_f32_16x16x32_fp8_fp8 v[136:139], v[116:117], v[244:245], 0
	v_mfma_f32_16x16x32_fp8_fp8 v[116:119], v[118:119], v[246:247], v[136:139]
	s_nop 5
	s_waitcnt vmcnt(20)
	v_mfma_f32_16x16x32_fp8_fp8 v[116:119], v[132:133], v[240:241], v[116:119]
	v_max_f32_e32 v133, v126, v127
	v_max_f32_e32 v132, v130, v131
	v_max3_f32 v133, v124, v125, v133
	v_mfma_f32_16x16x32_fp8_fp8 v[116:119], v[134:135], v[242:243], v[116:119]
	v_max3_f32 v1, v1, v132, v133
	v_max_f32_e32 v132, v122, v123
	v_max3_f32 v132, v120, v121, v132
	s_nop 3
	s_nop 0
	v_max_f32_e32 v133, v118, v119
	v_max3_f32 v133, v116, v117, v133
	v_max3_f32 v1, v1, v132, v133
	v_mov_b32_e32 v132, v1
	s_nop 1
	v_permlane16_swap_b32_e32 v1, v132
	v_max_f32_e32 v1, v1, v132
	v_mov_b32_e32 v132, v1
	s_nop 1
	v_permlane32_swap_b32_e32 v1, v132
	v_max_f32_e32 v1, v1, v132
	v_mul_f32_e64 v1, v1, s76
	v_max_f32_e32 v1, v238, v1
	v_cndmask_b32_e64 v241, v238, v1, s[14:15]
	v_sub_f32_e32 v133, 0x41000000, v241
	v_fma_f32 v128, v128, s76, v133
	v_fma_f32 v129, v129, s76, v133
	v_fma_f32 v124, v124, s76, v133
	v_fma_f32 v125, v125, s76, v133
	v_exp_f32_e32 v128, v128
	v_exp_f32_e32 v129, v129
	v_exp_f32_e32 v124, v124
	v_exp_f32_e32 v125, v125
	v_sub_f32_e32 v1, v238, v241
	v_fma_f32 v130, v130, s76, v133
	v_fma_f32 v131, v131, s76, v133
	v_fma_f32 v126, v126, s76, v133
	v_fma_f32 v127, v127, s76, v133
	v_exp_f32_e32 v132, v1
	v_exp_f32_e32 v130, v130
	v_exp_f32_e32 v131, v131
	v_exp_f32_e32 v126, v126
	v_exp_f32_e32 v127, v127
	v_cvt_pk_fp8_f32 v136, v124, v125
	v_cvt_pk_fp8_f32 v1, v128, v129
	v_pk_mul_f32 v[42:43], v[42:43], v[132:133] op_sel_hi:[1,0]
	v_pk_mul_f32 v[40:41], v[40:41], v[132:133] op_sel_hi:[1,0]
	v_cvt_pk_fp8_f32 v136, v126, v127 op_sel:[0,0,1]
	v_cvt_pk_fp8_f32 v1, v130, v131 op_sel:[0,0,1]
	v_pk_mul_f32 v[34:35], v[34:35], v[132:133] op_sel_hi:[1,0]
	v_pk_mul_f32 v[32:33], v[32:33], v[132:133] op_sel_hi:[1,0]
	v_cndmask_b32_e64 v135, 0, v136, s[12:13]
	v_cndmask_b32_e64 v134, 0, v1, s[12:13]
	v_pk_mul_f32 v[30:31], v[30:31], v[132:133] op_sel_hi:[1,0]
	v_pk_mul_f32 v[28:29], v[28:29], v[132:133] op_sel_hi:[1,0]
	v_fma_f32 v120, v120, s76, v133
	v_fma_f32 v121, v121, s76, v133
	v_mfma_f32_16x16x32_fp8_fp8 v[40:43], v[48:49], v[134:135], v[40:43]
	v_fma_f32 v48, v116, s76, v133
	v_pk_mul_f32 v[38:39], v[38:39], v[132:133] op_sel_hi:[1,0]
	v_pk_mul_f32 v[36:37], v[36:37], v[132:133] op_sel_hi:[1,0]
	v_mfma_f32_16x16x32_fp8_fp8 v[32:35], v[6:7], v[134:135], v[32:35]
	v_exp_f32_e32 v120, v120
	v_exp_f32_e32 v121, v121
	v_fma_f32 v122, v122, s76, v133
	v_mfma_f32_16x16x32_fp8_fp8 v[28:31], v[2:3], v[134:135], v[28:31]
	v_cndmask_b32_e64 v2, 0, v1, s[0:1]
	v_fma_f32 v1, v117, s76, v133
	v_cndmask_b32_e64 v3, 0, v136, s[0:1]
	v_mfma_f32_16x16x32_fp8_fp8 v[36:39], v[44:45], v[134:135], v[36:39]
	v_exp_f32_e32 v44, v48
	v_exp_f32_e32 v45, v1
	v_fma_f32 v1, v118, s76, v133
	v_exp_f32_e32 v48, v1
	v_fma_f32 v1, v119, s76, v133
	v_fma_f32 v123, v123, s76, v133
	v_exp_f32_e32 v49, v1
	s_waitcnt vmcnt(17)
	v_mfma_f32_16x16x32_fp8_fp8 v[32:35], v[104:105], v[2:3], v[32:35]
	v_exp_f32_e32 v122, v122
	v_exp_f32_e32 v123, v123
	v_cvt_pk_fp8_f32 v104, v44, v45
	v_cvt_pk_fp8_f32 v1, v120, v121
	v_mfma_f32_16x16x32_fp8_fp8 v[36:39], v[108:109], v[2:3], v[36:39]
	v_cvt_pk_fp8_f32 v104, v48, v49 op_sel:[0,0,1]
	v_cvt_pk_fp8_f32 v1, v122, v123 op_sel:[0,0,1]
	v_mfma_f32_16x16x32_fp8_fp8 v[40:43], v[112:113], v[2:3], v[40:43]
	s_waitcnt vmcnt(16)
	v_mfma_f32_16x16x32_fp8_fp8 v[28:31], v[100:101], v[2:3], v[28:31]
	v_cndmask_b32_e64 v3, 0, v104, s[12:13]
	v_cndmask_b32_e64 v2, 0, v1, s[12:13]
	s_nop 1
	v_mfma_f32_16x16x32_fp8_fp8 v[36:39], v[46:47], v[2:3], v[36:39]
	v_mfma_f32_16x16x32_fp8_fp8 v[6:9], v[8:9], v[2:3], v[32:35]
	s_nop 2
	v_pk_add_f32 v[34:35], v[124:125], v[128:129]
	v_pk_add_f32 v[32:33], v[126:127], v[130:131]
	v_mfma_f32_16x16x32_fp8_fp8 v[40:43], v[50:51], v[2:3], v[40:43]
	v_add_f32_e64 v32, v122, v32
	v_add_f32_e64 v33, v123, v33
	v_mfma_f32_16x16x32_fp8_fp8 v[2:5], v[4:5], v[2:3], v[28:31]
	v_add_f32_e64 v32, v48, v32
	v_add_f32_e64 v33, v49, v33
	s_nop 0
	v_pk_add_f32 v[28:29], v[120:121], v[34:35]
	v_cndmask_b32_e64 v31, 0, v104, s[0:1]
	v_pk_add_f32 v[28:29], v[44:45], v[28:29]
	v_cndmask_b32_e64 v30, 0, v1, s[0:1]
	v_pk_mov_b32 v[34:35], v[28:29], v[32:33] op_sel:[1,0]
	v_mov_b32_e32 v29, v33
	v_pk_add_f32 v[28:29], v[34:35], v[28:29]
	v_mfma_f32_16x16x32_fp8_fp8 v[40:43], v[114:115], v[30:31], v[40:43]
	v_add_f32_e32 v1, v28, v29
	v_cndmask_b32_e64 v242, 0, v1, s[14:15]
	v_fmac_f32_e32 v242, v237, v132
	v_mfma_f32_16x16x32_fp8_fp8 v[36:39], v[110:111], v[30:31], v[36:39]
	v_mfma_f32_16x16x32_fp8_fp8 v[32:35], v[106:107], v[30:31], v[6:9]
	v_mfma_f32_16x16x32_fp8_fp8 v[28:31], v[102:103], v[30:31], v[2:5]
.LBB0_601:
	s_andn2_saveexec_b64 s[12:13], s[22:23]
	s_cbranch_execz .LBB0_576
	v_cmp_ge_i32_e64 s[0:1], v1, v229
	s_and_saveexec_b64 s[14:15], s[0:1]
	s_xor_b64 s[14:15], exec, s[14:15]
	s_cbranch_execz .LBB0_604
	s_cmp_eq_u32 s99, 16
	s_cbranch_scc1 .Lwkd_4
	s_cmp_eq_u32 s99, 8
	s_cbranch_scc1 .Lwk8_4
	s_waitcnt vmcnt(0)
	s_branch .Lwkd_4

.Lwkd_4:
	s_waitcnt vmcnt(16)
	v_mfma_f32_16x16x32_fp8_fp8 v[100:103], v[128:129], v[150:151], 0
	v_lshl_or_b32 v1, v1, 6, v212
	v_cmp_le_i32_e64 s[0:1], v1, v228
	v_mfma_f32_16x16x32_fp8_fp8 v[100:103], v[130:131], v[10:11], v[100:103]
	v_mfma_f32_16x16x32_fp8_fp8 v[104:107], v[124:125], v[150:151], 0
	v_mfma_f32_16x16x32_fp8_fp8 v[104:107], v[126:127], v[10:11], v[104:107]
	s_nop 5
	v_mul_f32_e64 v114, v100, s76
	v_mul_f32_e64 v115, v101, s76
	v_pk_mul_f32 v[112:113], v[102:103], s[76:77] op_sel_hi:[1,0]
	v_cndmask_b32_e64 v114, v220, v114, s[0:1]
	v_mfma_f32_16x16x32_fp8_fp8 v[108:111], v[120:121], v[150:151], 0
	v_cmp_lt_i32_e64 s[0:1], v1, v228
	v_pk_mul_f32 v[104:105], v[104:105], s[76:77] op_sel_hi:[1,0]
	v_pk_mul_f32 v[106:107], v[106:107], s[76:77] op_sel_hi:[1,0]
	v_mfma_f32_16x16x32_fp8_fp8 v[100:103], v[116:117], v[150:151], 0
	v_or_b32_e32 v116, 2, v1
	v_cndmask_b32_e64 v115, v220, v115, s[0:1]
	v_cmp_le_i32_e64 s[0:1], v116, v228
	v_or_b32_e32 v116, 3, v1
	v_mfma_f32_16x16x32_fp8_fp8 v[108:111], v[122:123], v[10:11], v[108:111]
	v_cndmask_b32_e64 v112, v220, v112, s[0:1]
	v_cmp_le_i32_e64 s[0:1], v116, v228
	v_or_b32_e32 v116, 16, v1
	v_mfma_f32_16x16x32_fp8_fp8 v[100:103], v[118:119], v[10:11], v[100:103]
	v_cndmask_b32_e64 v113, v220, v113, s[0:1]
	v_cmp_le_i32_e64 s[0:1], v116, v228
	v_or_b32_e32 v116, 17, v1
	s_nop 0
	v_pk_mul_f32 v[108:109], v[108:109], s[76:77] op_sel_hi:[1,0]
	v_cndmask_b32_e64 v104, v220, v104, s[0:1]
	v_cmp_le_i32_e64 s[0:1], v116, v228
	v_or_b32_e32 v116, 18, v1
	v_pk_mul_f32 v[110:111], v[110:111], s[76:77] op_sel_hi:[1,0]
	v_cndmask_b32_e64 v105, v220, v105, s[0:1]
	v_cmp_le_i32_e64 s[0:1], v116, v228
	v_or_b32_e32 v116, 19, v1
	v_pk_mul_f32 v[100:101], v[100:101], s[76:77] op_sel_hi:[1,0]
	v_cndmask_b32_e64 v106, v220, v106, s[0:1]
	v_cmp_le_i32_e64 s[0:1], v116, v228
	v_or_b32_e32 v116, 32, v1
	v_pk_mul_f32 v[102:103], v[102:103], s[76:77] op_sel_hi:[1,0]
	v_cndmask_b32_e64 v107, v220, v107, s[0:1]
	v_cmp_le_i32_e64 s[0:1], v116, v228
	s_nop 1
	v_cndmask_b32_e64 v116, v220, v108, s[0:1]
	v_or_b32_e32 v108, 33, v1
	v_cmp_le_i32_e64 s[0:1], v108, v228
	v_or_b32_e32 v108, 34, v1
	s_nop 0
	v_cndmask_b32_e64 v117, v220, v109, s[0:1]
	v_cmp_le_i32_e64 s[0:1], v108, v228
	v_or_b32_e32 v108, 35, v1
	s_nop 0
	v_cndmask_b32_e64 v118, v220, v110, s[0:1]
	v_cmp_le_i32_e64 s[0:1], v108, v228
	v_or_b32_e32 v108, 48, v1
	s_nop 0
	v_cndmask_b32_e64 v119, v220, v111, s[0:1]
	v_cmp_le_i32_e64 s[0:1], v108, v228
	s_nop 1
	v_cndmask_b32_e64 v120, v220, v100, s[0:1]
	v_or_b32_e32 v100, 49, v1
	v_cmp_le_i32_e64 s[0:1], v100, v228
	v_or_b32_e32 v100, 50, v1
	v_or_b32_e32 v1, 51, v1
	v_cndmask_b32_e64 v121, v220, v101, s[0:1]
	v_cmp_le_i32_e64 s[0:1], v100, v228
	v_max_f32_e32 v100, v114, v115
	v_max_f32_e32 v101, v112, v113
	v_cndmask_b32_e64 v122, v220, v102, s[0:1]
	v_cmp_le_i32_e64 s[0:1], v1, v228
	v_max_f32_e32 v102, v106, v107
	v_max3_f32 v102, v104, v105, v102
	v_cndmask_b32_e64 v1, v220, v103, s[0:1]
	v_max3_f32 v100, v100, v101, v102
	v_max_f32_e32 v101, v118, v119
	v_max_f32_e32 v102, v122, v1
	v_max3_f32 v101, v116, v117, v101
	v_max3_f32 v102, v120, v121, v102
	v_max3_f32 v100, v100, v101, v102
	v_mov_b32_e32 v101, v100
	v_cmp_lt_f32_e64 s[0:1], s83, v114
	s_nop 1
	v_permlane16_swap_b32_e32 v100, v101
	v_max_f32_e32 v100, v100, v101
	v_mov_b32_e32 v101, v100
	s_nop 1
	v_permlane32_swap_b32_e32 v100, v101
	v_max3_f32 v241, v238, v100, v101
	v_sub_f32_e32 v123, 0x41000000, v241
	v_add_f32_e32 v100, v114, v123
	v_exp_f32_e32 v100, v100
	v_add_f32_e32 v101, v112, v123
	v_exp_f32_e32 v101, v101
	v_add_f32_e32 v102, v104, v123
	v_cndmask_b32_e64 v108, 0, v100, s[0:1]
	v_add_f32_e32 v100, v115, v123
	v_exp_f32_e32 v100, v100
	v_cmp_lt_f32_e64 s[0:1], s83, v115
	v_exp_f32_e32 v110, v102
	v_add_f32_e32 v111, v106, v123
	v_cndmask_b32_e64 v109, 0, v100, s[0:1]
	v_cmp_lt_f32_e64 s[0:1], s83, v112
	v_exp_f32_e32 v111, v111
	v_add_f32_e32 v112, v118, v123
	v_cndmask_b32_e64 v100, 0, v101, s[0:1]
	v_add_f32_e32 v101, v113, v123
	v_exp_f32_e32 v101, v101
	v_cmp_lt_f32_e64 s[0:1], s83, v113
	v_exp_f32_e32 v112, v112
	v_add_f32_e32 v113, v119, v123
	v_cndmask_b32_e64 v101, 0, v101, s[0:1]
	v_cmp_lt_f32_e64 s[0:1], s83, v104
	v_sub_f32_e32 v124, v238, v241
	v_pk_add_f32 v[102:103], v[108:109], 0 op_sel_hi:[1,0]
	v_cndmask_b32_e64 v104, 0, v110, s[0:1]
	v_add_f32_e32 v110, v105, v123
	v_exp_f32_e32 v110, v110
	v_cmp_lt_f32_e64 s[0:1], s83, v105
	v_exp_f32_e32 v113, v113
	v_add_f32_e32 v114, v120, v123
	v_cndmask_b32_e64 v105, 0, v110, s[0:1]
	v_cmp_lt_f32_e64 s[0:1], s83, v106
	v_add_f32_e32 v110, v107, v123
	v_exp_f32_e32 v110, v110
	v_cndmask_b32_e64 v106, 0, v111, s[0:1]
	v_add_f32_e32 v111, v116, v123
	v_exp_f32_e32 v111, v111
	v_cmp_lt_f32_e64 s[0:1], s83, v107
	v_exp_f32_e32 v114, v114
	v_add_f32_e32 v115, v121, v123
	v_cndmask_b32_e64 v107, 0, v110, s[0:1]
	v_cmp_lt_f32_e64 s[0:1], s83, v116
	v_exp_f32_e32 v115, v115
	v_add_f32_e32 v116, v122, v123
	v_cndmask_b32_e64 v110, 0, v111, s[0:1]
	v_add_f32_e32 v111, v117, v123
	v_exp_f32_e32 v111, v111
	v_cmp_lt_f32_e64 s[0:1], s83, v117
	v_exp_f32_e32 v116, v116
	s_nop 0
	v_cndmask_b32_e64 v111, 0, v111, s[0:1]
	v_cmp_lt_f32_e64 s[0:1], s83, v118
	v_mov_b32_e32 v118, 0
	v_cvt_pk_fp8_f32 v118, v108, v109
	v_cndmask_b32_e64 v112, 0, v112, s[0:1]
	v_cmp_lt_f32_e64 s[0:1], s83, v119
	v_mov_b32_e32 v119, 0
	v_cvt_pk_fp8_f32 v119, v104, v105
	v_add_f32_e32 v109, v1, v123
	v_exp_f32_e32 v108, v124
	v_exp_f32_e32 v109, v109
	v_cvt_pk_fp8_f32 v118, v100, v101 op_sel:[0,0,1]
	v_cvt_pk_fp8_f32 v119, v106, v107 op_sel:[0,0,1]
	v_cndmask_b32_e64 v113, 0, v113, s[0:1]
	v_cmp_lt_f32_e64 s[0:1], s83, v120
	v_pk_mul_f32 v[34:35], v[34:35], v[108:109] op_sel_hi:[1,0]
	v_pk_mul_f32 v[32:33], v[32:33], v[108:109] op_sel_hi:[1,0]
	v_cndmask_b32_e64 v114, 0, v114, s[0:1]
	v_cmp_lt_f32_e64 s[0:1], s83, v121
	v_mfma_f32_16x16x32_fp8_fp8 v[32:35], v[6:7], v[118:119], v[32:35]
	v_mov_b32_e32 v6, 0
	v_cndmask_b32_e64 v115, 0, v115, s[0:1]
	v_mov_b32_e32 v7, 0
	v_cvt_pk_fp8_f32 v6, v110, v111
	v_cvt_pk_fp8_f32 v7, v114, v115
	v_cmp_lt_f32_e64 s[0:1], s83, v122
	v_pk_mul_f32 v[38:39], v[38:39], v[108:109] op_sel_hi:[1,0]
	v_pk_mul_f32 v[36:37], v[36:37], v[108:109] op_sel_hi:[1,0]
	v_cndmask_b32_e64 v116, 0, v116, s[0:1]
	v_cmp_lt_f32_e64 s[0:1], s83, v1
	v_pk_mul_f32 v[30:31], v[30:31], v[108:109] op_sel_hi:[1,0]
	v_pk_mul_f32 v[28:29], v[28:29], v[108:109] op_sel_hi:[1,0]
	v_cndmask_b32_e64 v117, 0, v109, s[0:1]
	v_mfma_f32_16x16x32_fp8_fp8 v[36:39], v[44:45], v[118:119], v[36:39]
	v_cvt_pk_fp8_f32 v6, v112, v113 op_sel:[0,0,1]
	v_cvt_pk_fp8_f32 v7, v116, v117 op_sel:[0,0,1]
	v_pk_add_f32 v[44:45], v[104:105], v[102:103]
	v_mfma_f32_16x16x32_fp8_fp8 v[28:31], v[2:3], v[118:119], v[28:31]
	v_add_f32_e64 v2, v100, 0
	v_add_f32_e64 v3, v101, 0
	v_pk_mul_f32 v[42:43], v[42:43], v[108:109] op_sel_hi:[1,0]
	v_pk_add_f32 v[2:3], v[106:107], v[2:3]
	v_pk_mul_f32 v[40:41], v[40:41], v[108:109] op_sel_hi:[1,0]
	v_pk_add_f32 v[44:45], v[110:111], v[44:45]
	v_pk_add_f32 v[2:3], v[112:113], v[2:3]
	v_mfma_f32_16x16x32_fp8_fp8 v[40:43], v[48:49], v[118:119], v[40:43]
	v_add_f32_e64 v2, v116, v2
	v_add_f32_e64 v3, v117, v3
	v_pk_add_f32 v[44:45], v[114:115], v[44:45]
	v_mfma_f32_16x16x32_fp8_fp8 v[36:39], v[46:47], v[6:7], v[36:39]
	v_pk_mov_b32 v[46:47], v[44:45], v[2:3] op_sel:[1,0]
	v_mov_b32_e32 v45, v3
	v_pk_add_f32 v[2:3], v[46:47], v[44:45]
	v_mfma_f32_16x16x32_fp8_fp8 v[40:43], v[50:51], v[6:7], v[40:43]
	v_add_f32_e32 v242, v2, v3
	v_fmac_f32_e32 v242, v237, v108
	v_mfma_f32_16x16x32_fp8_fp8 v[32:35], v[8:9], v[6:7], v[32:35]
	v_mfma_f32_16x16x32_fp8_fp8 v[28:31], v[4:5], v[6:7], v[28:31]

.Lwkd_5:
	s_waitcnt vmcnt(16)
	v_mfma_f32_16x16x32_fp8_fp8 v[100:103], v[128:129], v[150:151], 0
	v_mfma_f32_16x16x32_fp8_fp8 v[100:103], v[130:131], v[10:11], v[100:103]
	v_mfma_f32_16x16x32_fp8_fp8 v[104:107], v[124:125], v[150:151], 0
	v_mfma_f32_16x16x32_fp8_fp8 v[108:111], v[120:121], v[150:151], 0
	s_nop 5
	v_mul_f32_e64 v112, v102, s76
	v_mul_f32_e64 v113, v103, s76
	v_pk_mul_f32 v[114:115], v[100:101], s[76:77] op_sel_hi:[1,0]
	v_mfma_f32_16x16x32_fp8_fp8 v[100:103], v[116:117], v[150:151], 0
	v_max_f32_e32 v1, v114, v115
	v_max_f32_e32 v116, v112, v113
	v_mfma_f32_16x16x32_fp8_fp8 v[104:107], v[126:127], v[10:11], v[104:107]
	v_mfma_f32_16x16x32_fp8_fp8 v[108:111], v[122:123], v[10:11], v[108:111]
	v_mfma_f32_16x16x32_fp8_fp8 v[100:103], v[118:119], v[10:11], v[100:103]
	s_nop 5
	v_mul_f32_e64 v106, v106, s76
	v_mul_f32_e64 v107, v107, s76
	v_pk_mul_f32 v[104:105], v[104:105], s[76:77] op_sel_hi:[1,0]
	v_max_f32_e32 v117, v106, v107
	v_pk_mul_f32 v[110:111], v[110:111], s[76:77] op_sel_hi:[1,0]
	v_max3_f32 v117, v104, v105, v117
	v_pk_mul_f32 v[102:103], v[102:103], s[76:77] op_sel_hi:[1,0]
	v_pk_mul_f32 v[108:109], v[108:109], s[76:77] op_sel_hi:[1,0]
	v_pk_mul_f32 v[100:101], v[100:101], s[76:77] op_sel_hi:[1,0]
	v_max3_f32 v1, v1, v116, v117
	v_max_f32_e32 v116, v110, v111
	v_max_f32_e32 v117, v102, v103
	v_max3_f32 v116, v108, v109, v116
	v_max3_f32 v117, v100, v101, v117
	v_max3_f32 v1, v1, v116, v117
	v_mov_b32_e32 v116, v1
	v_mov_b32_e32 v118, 0
	v_mov_b32_e32 v119, 0
	s_nop 1
	v_permlane16_swap_b32_e32 v1, v116
	v_max_f32_e32 v1, v1, v116
	v_mov_b32_e32 v116, v1
	s_nop 1
	v_permlane32_swap_b32_e32 v1, v116
	v_max3_f32 v241, v238, v1, v116
	v_sub_f32_e32 v120, 0x41000000, v241
	v_add_f32_e32 v114, v114, v120
	v_add_f32_e32 v115, v115, v120
	v_add_f32_e32 v104, v104, v120
	v_add_f32_e32 v105, v105, v120
	v_exp_f32_e32 v114, v114
	v_exp_f32_e32 v115, v115
	v_exp_f32_e32 v104, v104
	v_exp_f32_e32 v105, v105
	v_add_f32_e32 v112, v112, v120
	v_add_f32_e32 v113, v113, v120
	v_add_f32_e32 v106, v106, v120
	v_add_f32_e32 v107, v107, v120
	v_exp_f32_e32 v112, v112
	v_exp_f32_e32 v113, v113
	v_exp_f32_e32 v106, v106
	v_exp_f32_e32 v107, v107
	v_cvt_pk_fp8_f32 v118, v114, v115
	v_cvt_pk_fp8_f32 v119, v104, v105
	v_sub_f32_e32 v1, v238, v241
	v_pk_add_f32 v[116:117], v[114:115], 0 op_sel_hi:[1,0]
	v_exp_f32_e32 v114, v1
	v_add_f32_e32 v108, v108, v120
	v_add_f32_e32 v109, v109, v120
	v_add_f32_e32 v100, v100, v120
	v_add_f32_e32 v101, v101, v120
	v_cvt_pk_fp8_f32 v118, v112, v113 op_sel:[0,0,1]
	v_cvt_pk_fp8_f32 v119, v106, v107 op_sel:[0,0,1]
	v_exp_f32_e32 v108, v108
	v_exp_f32_e32 v109, v109
	v_exp_f32_e32 v100, v100
	v_exp_f32_e32 v101, v101
	v_pk_mul_f32 v[34:35], v[34:35], v[114:115] op_sel_hi:[1,0]
	v_pk_mul_f32 v[32:33], v[32:33], v[114:115] op_sel_hi:[1,0]
	v_add_f32_e32 v110, v110, v120
	v_add_f32_e32 v111, v111, v120
	v_add_f32_e32 v102, v102, v120
	v_add_f32_e32 v1, v103, v120
	v_mfma_f32_16x16x32_fp8_fp8 v[32:35], v[6:7], v[118:119], v[32:35]
	v_mov_b32_e32 v6, 0
	v_mov_b32_e32 v7, 0
	v_exp_f32_e32 v110, v110
	v_exp_f32_e32 v111, v111
	v_exp_f32_e32 v102, v102
	v_exp_f32_e32 v103, v1
	v_cvt_pk_fp8_f32 v6, v108, v109
	v_cvt_pk_fp8_f32 v7, v100, v101
	v_pk_mul_f32 v[42:43], v[42:43], v[114:115] op_sel_hi:[1,0]
	v_pk_mul_f32 v[40:41], v[40:41], v[114:115] op_sel_hi:[1,0]
	v_pk_mul_f32 v[38:39], v[38:39], v[114:115] op_sel_hi:[1,0]
	v_pk_mul_f32 v[36:37], v[36:37], v[114:115] op_sel_hi:[1,0]
	v_pk_mul_f32 v[30:31], v[30:31], v[114:115] op_sel_hi:[1,0]
	v_pk_mul_f32 v[28:29], v[28:29], v[114:115] op_sel_hi:[1,0]
	v_mfma_f32_16x16x32_fp8_fp8 v[40:43], v[48:49], v[118:119], v[40:43]
	v_cvt_pk_fp8_f32 v6, v110, v111 op_sel:[0,0,1]
	v_cvt_pk_fp8_f32 v7, v102, v103 op_sel:[0,0,1]
	v_mfma_f32_16x16x32_fp8_fp8 v[36:39], v[44:45], v[118:119], v[36:39]
	v_add_f32_e64 v44, v104, v116
	v_add_f32_e64 v45, v105, v117
	v_pk_add_f32 v[44:45], v[108:109], v[44:45]
	v_mfma_f32_16x16x32_fp8_fp8 v[28:31], v[2:3], v[118:119], v[28:31]
	v_add_f32_e64 v2, v112, 0
	v_add_f32_e64 v3, v113, 0
	v_pk_add_f32 v[44:45], v[100:101], v[44:45]
	v_pk_add_f32 v[2:3], v[106:107], v[2:3]
	v_mfma_f32_16x16x32_fp8_fp8 v[40:43], v[50:51], v[6:7], v[40:43]
	v_add_f32_e64 v2, v110, v2
	v_add_f32_e64 v3, v111, v3
	v_pk_add_f32 v[2:3], v[102:103], v[2:3]
	v_mfma_f32_16x16x32_fp8_fp8 v[36:39], v[46:47], v[6:7], v[36:39]
	v_pk_mov_b32 v[46:47], v[44:45], v[2:3] op_sel:[1,0]
	v_mov_b32_e32 v45, v3
	v_pk_add_f32 v[2:3], v[46:47], v[44:45]
	v_mfma_f32_16x16x32_fp8_fp8 v[32:35], v[8:9], v[6:7], v[32:35]
	v_add_f32_e32 v242, v2, v3
	v_fmac_f32_e32 v242, v237, v114
	v_mfma_f32_16x16x32_fp8_fp8 v[28:31], v[4:5], v[6:7], v[28:31]
	s_branch .LBB0_575

.LBB0_862:
	s_or_b64 exec, exec, s[0:1]
	s_cmpk_lt_i32 s2, 0x1000
	s_cselect_b64 s[0:1], -1, 0
	v_mov_b32_e32 v0, v191
	s_and_b64 vcc, exec, s[0:1]
	s_waitcnt lgkmcnt(0)
	s_barrier
	s_cbranch_vccz .LBB0_867
	v_lshlrev_b32_e32 v1, 3, v0
	v_and_b32_e32 v1, 0x78, v1
	v_lshlrev_b32_e32 v2, 1, v1
	v_mov_b32_e32 v3, 0
	v_and_b32_e32 v4, 0x7f, v0
	v_lshl_add_u64 v[8:9], s[14:15], 0, v[2:3]
	v_lshlrev_b32_e32 v2, 2, v4
	v_lshl_add_u64 v[10:11], s[30:31], 0, v[2:3]
	v_add_u32_e32 v22, 16, v2
	v_mul_u32_u24_e32 v2, 0x8c, v4
	v_ashrrev_i32_e32 v4, 3, v0
	v_ashrrev_i32_e32 v5, 7, v0
	v_lshlrev_b32_e32 v4, 1, v4
	v_lshlrev_b32_e32 v20, 4, v5
	v_cmp_lt_i32_e64 s[4:5], 0, v5
	v_cmp_lt_i32_e64 s[6:7], 1, v5
	v_cmp_lt_i32_e64 s[8:9], 2, v5
	v_cmp_lt_i32_e64 s[10:11], 3, v5
	v_and_b32_e32 v4, 0xffffffe0, v4
	v_ashrrev_i32_e32 v5, 2, v0
	v_add3_u32 v23, v22, v2, v4
	v_and_b32_e32 v4, -16, v5
	v_bfi_b32 v5, -16, v5, v0
	s_movk_i32 s18, 0x90
	v_mul_lo_u32 v5, v5, s18
	v_bfe_u32 v2, v0, 4, 2
	v_add_u32_e32 v7, 16, v5
	v_ashrrev_i32_e32 v5, 31, v4
	v_ashrrev_i32_e32 v13, 4, v0
	v_and_b32_e32 v12, 15, v0
	v_lshlrev_b32_e32 v17, 4, v2
	v_lshl_add_u64 v[4:5], v[4:5], 1, s[28:29]
	v_lshlrev_b32_e32 v2, 3, v2
	s_add_u32 s16, s84, 0x1db00000
	s_movk_i32 s12, 0x80
	v_lshl_add_u32 v6, v13, 1, 16
	v_add_u32_e32 v18, 16, v17
	v_lshl_add_u64 v[14:15], v[4:5], 0, v[2:3]
	v_mul_u32_u24_e32 v1, 0x90, v1
	v_mul_u32_u24_e32 v2, 0x90, v12
	s_addc_u32 s17, s85, 0
	v_lshl_add_u32 v21, v0, 2, 16
	s_mov_b32 s19, 0
	v_cmp_gt_u32_e64 s[12:13], s12, v0
	s_lshl_b32 s24, s2, 6
	s_lshl_b32 s25, s86, 6
	v_lshl_add_u32 v16, s2, 7, v0
	s_lshl_b32 s27, s86, 7
	s_mov_b32 s34, 0x10000
	v_add_u32_e32 v24, v6, v1
	v_add_u32_e32 v25, v7, v17
	v_add_u32_e32 v26, v18, v2
	s_movk_i32 s35, 0x2000
	s_movk_i32 s36, 0x4000
	s_movk_i32 s37, 0x6000
	s_mov_b32 s38, s97
	s_mov_b32 s20, s2
	s_and_b32 s18, s38, 0xffffc000
	s_and_b32 s21, s24, 0x3fc0
	s_or_b32 s21, s18, s21
	s_lshr_b32 s18, s20, 1
	s_and_b32 s22, s18, 0x380
	v_add_u32_e32 v2, s21, v20
	s_lshl_b32 s18, s22, 1
	v_or_b32_e32 v38, 7, v2
	v_lshl_add_u64 v[0:1], v[8:9], 0, s[18:19]
	s_lshl_b32 s18, s22, 2
	v_ashrrev_i32_e32 v3, 31, v2
	v_or_b32_e32 v18, 1, v2
	v_or_b32_e32 v28, 2, v2
	v_or_b32_e32 v30, 3, v2
	v_or_b32_e32 v32, 4, v2
	v_or_b32_e32 v34, 5, v2
	v_or_b32_e32 v36, 6, v2
	v_ashrrev_i32_e32 v39, 31, v38
	v_lshl_add_u64 v[4:5], v[10:11], 0, s[18:19]
	v_lshlrev_b64 v[6:7], 12, v[2:3]
	v_ashrrev_i32_e32 v19, 31, v18
	v_ashrrev_i32_e32 v29, 31, v28
	v_ashrrev_i32_e32 v31, 31, v30
	v_ashrrev_i32_e32 v33, 31, v32
	v_ashrrev_i32_e32 v35, 31, v34
	v_ashrrev_i32_e32 v37, 31, v36
	v_lshlrev_b64 v[38:39], 12, v[38:39]
	v_lshl_add_u64 v[6:7], v[4:5], 0, v[6:7]
	v_lshlrev_b64 v[18:19], 12, v[18:19]
	v_lshlrev_b64 v[28:29], 12, v[28:29]
	v_lshlrev_b64 v[30:31], 12, v[30:31]
	v_lshlrev_b64 v[32:33], 12, v[32:33]
	v_lshlrev_b64 v[34:35], 12, v[34:35]
	v_lshlrev_b64 v[36:37], 12, v[36:37]
	v_lshl_add_u64 v[38:39], v[4:5], 0, v[38:39]
	v_lshl_add_u64 v[18:19], v[4:5], 0, v[18:19]
	v_lshl_add_u64 v[28:29], v[4:5], 0, v[28:29]
	v_lshl_add_u64 v[30:31], v[4:5], 0, v[30:31]
	v_lshl_add_u64 v[32:33], v[4:5], 0, v[32:33]
	v_lshl_add_u64 v[34:35], v[4:5], 0, v[34:35]
	v_lshl_add_u64 v[36:37], v[4:5], 0, v[36:37]
	global_load_dword v64, v[6:7], off
	global_load_dword v65, v[18:19], off
	global_load_dword v66, v[28:29], off
	global_load_dword v67, v[30:31], off
	global_load_dword v68, v[32:33], off
	global_load_dword v69, v[34:35], off
	global_load_dword v70, v[36:37], off
	global_load_dword v71, v[38:39], off
	v_or_b32_e32 v6, 8, v2
	v_ashrrev_i32_e32 v7, 31, v6
	v_or_b32_e32 v18, 9, v2
	v_or_b32_e32 v28, 10, v2
	v_or_b32_e32 v30, 11, v2
	v_or_b32_e32 v32, 12, v2
	v_or_b32_e32 v34, 13, v2
	v_or_b32_e32 v36, 14, v2
	v_or_b32_e32 v2, 15, v2
	v_lshlrev_b64 v[6:7], 12, v[6:7]
	v_ashrrev_i32_e32 v19, 31, v18
	v_ashrrev_i32_e32 v29, 31, v28
	v_ashrrev_i32_e32 v31, 31, v30
	v_ashrrev_i32_e32 v33, 31, v32
	v_ashrrev_i32_e32 v35, 31, v34
	v_ashrrev_i32_e32 v37, 31, v36
	v_ashrrev_i32_e32 v3, 31, v2
	v_lshl_add_u64 v[6:7], v[4:5], 0, v[6:7]
	v_lshlrev_b64 v[18:19], 12, v[18:19]
	v_lshlrev_b64 v[28:29], 12, v[28:29]
	v_lshlrev_b64 v[30:31], 12, v[30:31]
	v_lshlrev_b64 v[32:33], 12, v[32:33]
	v_lshlrev_b64 v[34:35], 12, v[34:35]
	v_lshlrev_b64 v[36:37], 12, v[36:37]
	v_lshlrev_b64 v[2:3], 12, v[2:3]
	v_lshl_add_u64 v[18:19], v[4:5], 0, v[18:19]
	v_lshl_add_u64 v[28:29], v[4:5], 0, v[28:29]
	v_lshl_add_u64 v[30:31], v[4:5], 0, v[30:31]
	v_lshl_add_u64 v[32:33], v[4:5], 0, v[32:33]
	v_lshl_add_u64 v[34:35], v[4:5], 0, v[34:35]
	v_lshl_add_u64 v[36:37], v[4:5], 0, v[36:37]
	v_lshl_add_u64 v[2:3], v[4:5], 0, v[2:3]
	global_load_dword v72, v[6:7], off
	global_load_dword v73, v[18:19], off
	global_load_dword v74, v[28:29], off
	global_load_dword v75, v[30:31], off
	global_load_dword v76, v[32:33], off
	global_load_dword v77, v[34:35], off
	global_load_dword v78, v[36:37], off
	global_load_dword v79, v[2:3], off
	v_add_u32_e32 v2, s21, v13
	v_ashrrev_i32_e32 v3, 31, v2
	v_lshlrev_b64 v[2:3], 11, v[2:3]
	v_lshl_add_u64 v[0:1], v[0:1], 0, v[2:3]
	v_add_co_u32_e32 v2, vcc, s34, v0
	s_nop 1
	v_addc_co_u32_e32 v3, vcc, 0, v1, vcc
	global_load_dwordx4 v[80:83], v[0:1], off
	global_load_dwordx4 v[84:87], v[2:3], off
	s_waitcnt vmcnt(0)
	s_branch .LBB0_865
.LBB0_864:
	s_or_b64 exec, exec, s[22:23]
	ds_write_b16 v24, v88 offset:34816
	ds_write_b16_d16_hi v24, v88 offset:34960
	ds_write_b16 v24, v89 offset:35104
	ds_write_b16_d16_hi v24, v89 offset:35248
	ds_write_b16 v24, v90 offset:35392
	ds_write_b16_d16_hi v24, v90 offset:35536
	ds_write_b16 v24, v91 offset:35680
	ds_write_b16_d16_hi v24, v91 offset:35824
	ds_write_b16 v24, v92 offset:34880
	ds_write_b16_d16_hi v24, v92 offset:35024
	ds_write_b16 v24, v93 offset:35168
	ds_write_b16_d16_hi v24, v93 offset:35312
	ds_write_b16 v24, v94 offset:35456
	ds_write_b16_d16_hi v24, v94 offset:35600
	ds_write_b16 v24, v95 offset:35744
	ds_write_b16_d16_hi v24, v95 offset:35888
	s_waitcnt lgkmcnt(0)
	s_barrier
	ds_read_b128 v[0:3], v25
	ds_read_b128 v[4:7], v25 offset:64
	ds_read_b128 v[28:31], v26 offset:34816
	ds_read_b128 v[32:35], v26 offset:34880
	s_waitcnt lgkmcnt(1)
	v_mfma_f32_16x16x32_bf16 v[28:31], v[0:3], v[28:31], 0
	ds_read_b128 v[36:39], v26 offset:37120
	s_ashr_i32 s21, s20, 31
	s_lshl_b64 s[22:23], s[20:21], 15
	s_waitcnt lgkmcnt(1)
	v_mfma_f32_16x16x32_bf16 v[28:31], v[4:7], v[32:35], v[28:31]
	ds_read_b128 v[32:35], v26 offset:37184
	v_lshl_or_b32 v40, v12, 8, s22
	v_mov_b32_e32 v41, s23
	s_waitcnt lgkmcnt(1)
	v_mfma_f32_16x16x32_bf16 v[36:39], v[0:3], v[36:39], 0
	v_lshl_add_u64 v[44:45], v[14:15], 0, v[40:41]
	s_nop 1
	v_cvt_pk_bf16_f32 v18, v28, v29
	v_cvt_pk_bf16_f32 v19, v30, v31
	ds_read_b128 v[28:31], v26 offset:39424
	s_waitcnt lgkmcnt(1)
	v_mfma_f32_16x16x32_bf16 v[32:35], v[4:7], v[32:35], v[36:39]
	ds_read_b128 v[40:43], v26 offset:41728
	global_store_dwordx2 v[44:45], v[18:19], off
	v_add_co_u32_e32 v46, vcc, s35, v44
	ds_read_b128 v[36:39], v26 offset:39488
	s_waitcnt lgkmcnt(2)
	v_mfma_f32_16x16x32_bf16 v[28:31], v[0:3], v[28:31], 0
	s_nop 1
	v_cvt_pk_bf16_f32 v18, v32, v33
	v_cvt_pk_bf16_f32 v19, v34, v35
	ds_read_b128 v[32:35], v26 offset:41792
	s_waitcnt lgkmcnt(1)
	v_mfma_f32_16x16x32_bf16 v[28:31], v[4:7], v[36:39], v[28:31]
	v_addc_co_u32_e32 v47, vcc, 0, v45, vcc
	global_store_dwordx2 v[46:47], v[18:19], off offset:-4096
	v_mfma_f32_16x16x32_bf16 v[36:39], v[0:3], v[40:43], 0
	ds_read_b128 v[40:43], v26 offset:44032
	s_nop 3
	v_cvt_pk_bf16_f32 v18, v28, v29
	v_cvt_pk_bf16_f32 v19, v30, v31
	s_waitcnt lgkmcnt(1)
	v_mfma_f32_16x16x32_bf16 v[32:35], v[4:7], v[32:35], v[36:39]
	ds_read_b128 v[28:31], v26 offset:46336
	global_store_dwordx2 v[46:47], v[18:19], off
	v_add_co_u32_e32 v46, vcc, s36, v44
	ds_read_b128 v[36:39], v26 offset:44096
	s_waitcnt lgkmcnt(2)
	v_mfma_f32_16x16x32_bf16 v[40:43], v[0:3], v[40:43], 0
	s_nop 1
	v_cvt_pk_bf16_f32 v18, v32, v33
	v_cvt_pk_bf16_f32 v19, v34, v35
	ds_read_b128 v[32:35], v26 offset:46400
	s_waitcnt lgkmcnt(1)
	v_mfma_f32_16x16x32_bf16 v[36:39], v[4:7], v[36:39], v[40:43]
	v_addc_co_u32_e32 v47, vcc, 0, v45, vcc
	global_store_dwordx2 v[46:47], v[18:19], off offset:-4096
	v_mfma_f32_16x16x32_bf16 v[28:31], v[0:3], v[28:31], 0
	ds_read_b128 v[40:43], v26 offset:48640
	s_nop 3
	v_cvt_pk_bf16_f32 v18, v36, v37
	v_cvt_pk_bf16_f32 v19, v38, v39
	s_waitcnt lgkmcnt(1)
	v_mfma_f32_16x16x32_bf16 v[28:31], v[4:7], v[32:35], v[28:31]
	ds_read_b128 v[32:35], v26 offset:48704
	global_store_dwordx2 v[46:47], v[18:19], off
	s_add_i32 s20, s20, s86
	s_waitcnt lgkmcnt(1)
	v_mfma_f32_16x16x32_bf16 v[36:39], v[0:3], v[40:43], 0
	v_add_co_u32_e32 v40, vcc, s37, v44
	s_nop 1
	v_cvt_pk_bf16_f32 v18, v28, v29
	v_cvt_pk_bf16_f32 v19, v30, v31
	s_waitcnt lgkmcnt(0)
	v_mfma_f32_16x16x32_bf16 v[28:31], v[4:7], v[32:35], v[36:39]
	ds_read_b128 v[32:35], v26 offset:50944
	v_addc_co_u32_e32 v41, vcc, 0, v45, vcc
	s_nop 0
	ds_read_b128 v[36:39], v26 offset:51008
	s_waitcnt lgkmcnt(1)
	v_mfma_f32_16x16x32_bf16 v[0:3], v[0:3], v[32:35], 0
	s_add_i32 s38, s38, s54
	s_add_i32 s24, s24, s25
	global_store_dwordx2 v[40:41], v[18:19], off offset:-4096
	s_waitcnt lgkmcnt(0)
	v_mfma_f32_16x16x32_bf16 v[0:3], v[4:7], v[36:39], v[0:3]
	v_cvt_pk_bf16_f32 v18, v28, v29
	v_cvt_pk_bf16_f32 v19, v30, v31
	s_cmpk_gt_i32 s20, 0xfff
	v_add_u32_e32 v16, s27, v16
	global_store_dwordx2 v[40:41], v[18:19], off
	s_nop 2
	v_cvt_pk_bf16_f32 v0, v0, v1
	v_cvt_pk_bf16_f32 v1, v2, v3
	v_add_co_u32_e32 v2, vcc, 0x7000, v44
	s_nop 1
	v_addc_co_u32_e32 v3, vcc, 0, v45, vcc
	global_store_dwordx2 v[2:3], v[0:1], off
	s_barrier
	s_cbranch_scc1 .LBB0_867
.LBB0_865:
	s_waitcnt vmcnt(8)
	v_mov_b32_e32 v17, v64
	v_mov_b32_e32 v27, v65
	v_mov_b32_e32 v40, v66
	v_mov_b32_e32 v41, v67
	v_mov_b32_e32 v42, v68
	v_mov_b32_e32 v43, v69
	v_mov_b32_e32 v44, v70
	v_mov_b32_e32 v96, v71
	v_mov_b32_e32 v45, v72
	v_mov_b32_e32 v46, v73
	v_mov_b32_e32 v47, v74
	v_mov_b32_e32 v48, v75
	v_mov_b32_e32 v49, v76
	v_mov_b32_e32 v50, v77
	v_mov_b32_e32 v51, v78
	v_mov_b32_e32 v52, v79
	v_mov_b64_e32 v[88:89], v[80:81]
	v_mov_b64_e32 v[90:91], v[82:83]
	v_mov_b64_e32 v[92:93], v[84:85]
	v_mov_b64_e32 v[94:95], v[86:87]
	s_add_i32 s68, s20, s86
	s_add_i32 s69, s24, s25
	s_add_i32 s70, s38, s54
	s_cmpk_gt_i32 s68, 0xfff
	s_cselect_b32 s68, s20, s68
	s_cselect_b32 s69, s24, s69
	s_cselect_b32 s70, s38, s70
	s_and_b32 s18, s70, 0xffffc000
	s_and_b32 s21, s69, 0x3fc0
	s_or_b32 s21, s18, s21
	s_lshr_b32 s18, s68, 1
	s_and_b32 s22, s18, 0x380
	v_add_u32_e32 v2, s21, v20
	s_lshl_b32 s18, s22, 1
	v_or_b32_e32 v38, 7, v2
	v_lshl_add_u64 v[0:1], v[8:9], 0, s[18:19]
	s_lshl_b32 s18, s22, 2
	v_ashrrev_i32_e32 v3, 31, v2
	v_or_b32_e32 v18, 1, v2
	v_or_b32_e32 v28, 2, v2
	v_or_b32_e32 v30, 3, v2
	v_or_b32_e32 v32, 4, v2
	v_or_b32_e32 v34, 5, v2
	v_or_b32_e32 v36, 6, v2
	v_ashrrev_i32_e32 v39, 31, v38
	v_lshl_add_u64 v[4:5], v[10:11], 0, s[18:19]
	v_lshlrev_b64 v[6:7], 12, v[2:3]
	v_ashrrev_i32_e32 v19, 31, v18
	v_ashrrev_i32_e32 v29, 31, v28
	v_ashrrev_i32_e32 v31, 31, v30
	v_ashrrev_i32_e32 v33, 31, v32
	v_ashrrev_i32_e32 v35, 31, v34
	v_ashrrev_i32_e32 v37, 31, v36
	v_lshlrev_b64 v[38:39], 12, v[38:39]
	v_lshl_add_u64 v[6:7], v[4:5], 0, v[6:7]
	v_lshlrev_b64 v[18:19], 12, v[18:19]
	v_lshlrev_b64 v[28:29], 12, v[28:29]
	v_lshlrev_b64 v[30:31], 12, v[30:31]
	v_lshlrev_b64 v[32:33], 12, v[32:33]
	v_lshlrev_b64 v[34:35], 12, v[34:35]
	v_lshlrev_b64 v[36:37], 12, v[36:37]
	v_lshl_add_u64 v[38:39], v[4:5], 0, v[38:39]
	v_lshl_add_u64 v[18:19], v[4:5], 0, v[18:19]
	v_lshl_add_u64 v[28:29], v[4:5], 0, v[28:29]
	v_lshl_add_u64 v[30:31], v[4:5], 0, v[30:31]
	v_lshl_add_u64 v[32:33], v[4:5], 0, v[32:33]
	v_lshl_add_u64 v[34:35], v[4:5], 0, v[34:35]
	v_lshl_add_u64 v[36:37], v[4:5], 0, v[36:37]
	global_load_dword v64, v[6:7], off
	global_load_dword v65, v[18:19], off
	global_load_dword v66, v[28:29], off
	global_load_dword v67, v[30:31], off
	global_load_dword v68, v[32:33], off
	global_load_dword v69, v[34:35], off
	global_load_dword v70, v[36:37], off
	global_load_dword v71, v[38:39], off
	v_or_b32_e32 v6, 8, v2
	v_ashrrev_i32_e32 v7, 31, v6
	v_or_b32_e32 v18, 9, v2
	v_or_b32_e32 v28, 10, v2
	v_or_b32_e32 v30, 11, v2
	v_or_b32_e32 v32, 12, v2
	v_or_b32_e32 v34, 13, v2
	v_or_b32_e32 v36, 14, v2
	v_or_b32_e32 v2, 15, v2
	v_lshlrev_b64 v[6:7], 12, v[6:7]
	v_ashrrev_i32_e32 v19, 31, v18
	v_ashrrev_i32_e32 v29, 31, v28
	v_ashrrev_i32_e32 v31, 31, v30
	v_ashrrev_i32_e32 v33, 31, v32
	v_ashrrev_i32_e32 v35, 31, v34
	v_ashrrev_i32_e32 v37, 31, v36
	v_ashrrev_i32_e32 v3, 31, v2
	v_lshl_add_u64 v[6:7], v[4:5], 0, v[6:7]
	v_lshlrev_b64 v[18:19], 12, v[18:19]
	v_lshlrev_b64 v[28:29], 12, v[28:29]
	v_lshlrev_b64 v[30:31], 12, v[30:31]
	v_lshlrev_b64 v[32:33], 12, v[32:33]
	v_lshlrev_b64 v[34:35], 12, v[34:35]
	v_lshlrev_b64 v[36:37], 12, v[36:37]
	v_lshlrev_b64 v[2:3], 12, v[2:3]
	v_lshl_add_u64 v[18:19], v[4:5], 0, v[18:19]
	v_lshl_add_u64 v[28:29], v[4:5], 0, v[28:29]
	v_lshl_add_u64 v[30:31], v[4:5], 0, v[30:31]
	v_lshl_add_u64 v[32:33], v[4:5], 0, v[32:33]
	v_lshl_add_u64 v[34:35], v[4:5], 0, v[34:35]
	v_lshl_add_u64 v[36:37], v[4:5], 0, v[36:37]
	v_lshl_add_u64 v[2:3], v[4:5], 0, v[2:3]
	global_load_dword v72, v[6:7], off
	global_load_dword v73, v[18:19], off
	global_load_dword v74, v[28:29], off
	global_load_dword v75, v[30:31], off
	global_load_dword v76, v[32:33], off
	global_load_dword v77, v[34:35], off
	global_load_dword v78, v[36:37], off
	global_load_dword v79, v[2:3], off
	v_add_u32_e32 v2, s21, v13
	v_ashrrev_i32_e32 v3, 31, v2
	v_lshlrev_b64 v[2:3], 11, v[2:3]
	v_lshl_add_u64 v[0:1], v[0:1], 0, v[2:3]
	v_add_co_u32_e32 v2, vcc, s34, v0
	s_nop 1
	v_addc_co_u32_e32 v3, vcc, 0, v1, vcc
	global_load_dwordx4 v[80:83], v[0:1], off
	global_load_dwordx4 v[84:87], v[2:3], off
	v_add_f32_e32 v18, 0, v17
	v_add_f32_e32 v32, v18, v27
	v_add_f32_e32 v34, v32, v40
	v_add_f32_e32 v35, v34, v41
	v_add_f32_e32 v36, v35, v42
	v_add_f32_e32 v37, v36, v43
	v_add_f32_e32 v38, v37, v44
	v_add_f32_e32 v19, v38, v96
	v_mul_f32_e32 v17, 0x3fb8aa3b, v17
	v_add_f32_e32 v53, v19, v45
	v_add_f32_e32 v54, v53, v46
	v_add_f32_e32 v55, v54, v47
	v_add_f32_e32 v56, v55, v48
	v_add_f32_e32 v57, v56, v49
	v_add_f32_e32 v58, v57, v50
	v_add_f32_e32 v59, v58, v51
	v_add_f32_e32 v60, v59, v52
	ds_write_b32 v21, v60 offset:53248
	s_waitcnt lgkmcnt(0)
	s_barrier
	ds_read2st64_b32 v[28:29], v22 offset0:208 offset1:210
	ds_read2st64_b32 v[30:31], v22 offset0:212 offset1:214
	s_waitcnt lgkmcnt(1)
	v_add_f32_e32 v28, 0, v28
	v_cndmask_b32_e64 v33, 0, v28, s[4:5]
	v_add_f32_e32 v61, v29, v33
	v_cndmask_b32_e64 v33, v33, v61, s[6:7]
	s_waitcnt lgkmcnt(0)
	v_add_f32_e32 v61, v30, v33
	v_cndmask_b32_e64 v33, v33, v61, s[8:9]
	v_add_f32_e32 v61, v31, v33
	v_cndmask_b32_e64 v33, v33, v61, s[10:11]
	v_add_f32_e32 v61, v18, v33
	v_add_f32_e32 v18, v28, v29
	v_add_f32_e32 v62, v32, v33
	v_add_f32_e32 v18, v18, v30
	v_mov_b32_e32 v32, v31
	v_pk_add_f32 v[18:19], v[18:19], v[32:33]
	v_exp_f32_e32 v28, v17
	v_sub_f32_e32 v17, v18, v61
	v_mul_f32_e32 v17, 0x3fb8aa3b, v17
	v_exp_f32_e32 v30, v17
	v_mul_f32_e32 v17, 0x3fb8aa3b, v27
	v_exp_f32_e32 v29, v17
	v_sub_f32_e32 v17, v18, v62
	v_mul_f32_e32 v17, 0x3fb8aa3b, v17
	v_add_f32_e32 v34, v34, v33
	v_exp_f32_e32 v31, v17
	v_mul_f32_e32 v17, 0x3fb8aa3b, v40
	v_exp_f32_e32 v32, v17
	v_sub_f32_e32 v17, v18, v34
	v_mul_f32_e32 v17, 0x3fb8aa3b, v17
	v_add_f32_e32 v35, v35, v33
	v_exp_f32_e32 v34, v17
	v_mul_f32_e32 v17, 0x3fb8aa3b, v41
	v_add_f32_e32 v36, v36, v33
	v_add_f32_e32 v37, v37, v33
	v_add_f32_e32 v38, v38, v33
	v_add_f32_e32 v53, v53, v33
	v_add_f32_e32 v54, v54, v33
	v_add_f32_e32 v55, v55, v33
	v_add_f32_e32 v56, v56, v33
	v_add_f32_e32 v57, v57, v33
	v_add_f32_e32 v58, v58, v33
	v_add_f32_e32 v59, v59, v33
	v_add_f32_e32 v60, v60, v33
	v_exp_f32_e32 v33, v17
	v_sub_f32_e32 v17, v18, v35
	v_mul_f32_e32 v17, 0x3fb8aa3b, v17
	v_exp_f32_e32 v35, v17
	v_pk_add_f32 v[28:29], v[28:29], 1.0 op_sel_hi:[1,0] neg_lo:[1,0] neg_hi:[1,0]
	v_mul_f32_e32 v17, 0x3fb8aa3b, v42
	v_pk_mul_f32 v[28:29], v[28:29], v[30:31]
	v_pk_add_f32 v[30:31], v[32:33], 1.0 op_sel_hi:[1,0] neg_lo:[1,0] neg_hi:[1,0]
	v_exp_f32_e32 v32, v17
	v_sub_f32_e32 v17, v18, v36
	v_mul_f32_e32 v17, 0x3fb8aa3b, v17
	v_pk_mul_f32 v[30:31], v[30:31], v[34:35]
	v_exp_f32_e32 v34, v17
	v_mul_f32_e32 v17, 0x3fb8aa3b, v43
	v_exp_f32_e32 v33, v17
	v_sub_f32_e32 v17, v18, v37
	v_mul_f32_e32 v17, 0x3fb8aa3b, v17
	v_exp_f32_e32 v35, v17
	v_mul_f32_e32 v17, 0x3fb8aa3b, v44
	v_exp_f32_e32 v36, v17
	v_sub_f32_e32 v17, v18, v38
	v_mul_f32_e32 v17, 0x3fb8aa3b, v17
	v_exp_f32_e32 v38, v17
	v_mul_f32_e32 v17, 0x3fb8aa3b, v96
	v_exp_f32_e32 v37, v17
	v_sub_f32_e32 v17, v18, v19
	v_mul_f32_e32 v17, 0x3fb8aa3b, v17
	v_exp_f32_e32 v39, v17
	v_pk_add_f32 v[32:33], v[32:33], 1.0 op_sel_hi:[1,0] neg_lo:[1,0] neg_hi:[1,0]
	v_mul_f32_e32 v17, 0x3fb8aa3b, v45
	v_pk_mul_f32 v[32:33], v[32:33], v[34:35]
	v_pk_add_f32 v[34:35], v[36:37], 1.0 op_sel_hi:[1,0] neg_lo:[1,0] neg_hi:[1,0]
	v_exp_f32_e32 v36, v17
	v_sub_f32_e32 v17, v18, v53
	v_mul_f32_e32 v17, 0x3fb8aa3b, v17
	v_pk_mul_f32 v[34:35], v[34:35], v[38:39]
	v_exp_f32_e32 v38, v17
	v_mul_f32_e32 v17, 0x3fb8aa3b, v46
	v_exp_f32_e32 v37, v17
	v_sub_f32_e32 v17, v18, v54
	v_mul_f32_e32 v17, 0x3fb8aa3b, v17
	v_exp_f32_e32 v39, v17
	v_mul_f32_e32 v17, 0x3fb8aa3b, v47
	v_exp_f32_e32 v40, v17
	v_sub_f32_e32 v17, v18, v55
	v_mul_f32_e32 v17, 0x3fb8aa3b, v17
	v_exp_f32_e32 v42, v17
	v_mul_f32_e32 v17, 0x3fb8aa3b, v48
	v_exp_f32_e32 v41, v17
	v_sub_f32_e32 v17, v18, v56
	v_mul_f32_e32 v17, 0x3fb8aa3b, v17
	v_exp_f32_e32 v43, v17
	v_pk_add_f32 v[36:37], v[36:37], 1.0 op_sel_hi:[1,0] neg_lo:[1,0] neg_hi:[1,0]
	v_mul_f32_e32 v17, 0x3fb8aa3b, v49
	v_pk_mul_f32 v[36:37], v[36:37], v[38:39]
	v_pk_add_f32 v[38:39], v[40:41], 1.0 op_sel_hi:[1,0] neg_lo:[1,0] neg_hi:[1,0]
	v_exp_f32_e32 v40, v17
	v_sub_f32_e32 v17, v18, v57
	v_mul_f32_e32 v17, 0x3fb8aa3b, v17
	v_pk_mul_f32 v[38:39], v[38:39], v[42:43]
	v_exp_f32_e32 v42, v17
	v_mul_f32_e32 v17, 0x3fb8aa3b, v50
	v_exp_f32_e32 v41, v17
	v_sub_f32_e32 v17, v18, v58
	v_mul_f32_e32 v17, 0x3fb8aa3b, v17
	v_exp_f32_e32 v43, v17
	v_mul_f32_e32 v17, 0x3fb8aa3b, v51
	v_exp_f32_e32 v44, v17
	v_sub_f32_e32 v17, v18, v59
	v_mul_f32_e32 v17, 0x3fb8aa3b, v17
	v_exp_f32_e32 v46, v17
	v_mul_f32_e32 v17, 0x3fb8aa3b, v52
	v_exp_f32_e32 v45, v17
	v_sub_f32_e32 v17, v18, v60
	v_mul_f32_e32 v17, 0x3fb8aa3b, v17
	v_exp_f32_e32 v47, v17
	v_pk_add_f32 v[40:41], v[40:41], 1.0 op_sel_hi:[1,0] neg_lo:[1,0] neg_hi:[1,0]
	v_cvt_pk_bf16_f32 v28, v28, v29
	v_pk_mul_f32 v[40:41], v[40:41], v[42:43]
	v_pk_add_f32 v[42:43], v[44:45], 1.0 op_sel_hi:[1,0] neg_lo:[1,0] neg_hi:[1,0]
	v_cvt_pk_bf16_f32 v29, v30, v31
	v_pk_mul_f32 v[42:43], v[42:43], v[46:47]
	v_cvt_pk_bf16_f32 v30, v32, v33
	v_cvt_pk_bf16_f32 v31, v34, v35
	ds_write_b128 v23, v[28:31]
	v_cvt_pk_bf16_f32 v28, v36, v37
	v_cvt_pk_bf16_f32 v29, v38, v39
	v_cvt_pk_bf16_f32 v30, v40, v41
	v_cvt_pk_bf16_f32 v31, v42, v43
	ds_write_b128 v23, v[28:31] offset:16
	s_and_saveexec_b64 s[22:23], s[12:13]
	s_cbranch_execz .LBB0_864
	v_mul_f32_e32 v17, 0x3fb8aa3b, v18
	v_exp_f32_e32 v27, v17
	v_ashrrev_i32_e32 v17, 31, v16
	v_lshl_add_u64 v[18:19], v[16:17], 2, s[16:17]
	global_store_dword v[18:19], v27, off
	s_branch .LBB0_864
